# v19 with the GEMM K-loop LDS-DMA issue packed into the first eight register-fed MFMAs after the barrier
# speedup vs baseline: 1.0083x; 1.0083x over previous
.Lgsk0_loop:
	s_add_i32 s9, s8, 0xfffe8000
	s_and_b32 s10, s8, 0x18000
	s_waitcnt vmcnt(8) lgkmcnt(0)
	s_barrier
	s_and_b32 s9, s9, 0x18000
	s_add_i32 s10, s7, s10
	v_add_u32_e32 v112, s9, v135
	v_or_b32_e32 v139, s9, v137
	s_add_i32 s18, s10, 0x400
	s_add_i32 s11, s10, 0x800
	s_add_i32 s9, s10, 0xc00
	s_add_i32 s8, s8, 0x8000
	s_cmp_eq_u32 s8, 0x100000
	ds_read_b128 v[186:189], v112
	ds_read_b128 v[190:193], v112 offset:1024
	ds_read_b128 v[194:197], v112 offset:2048
	ds_read_b128 v[198:201], v112 offset:3072
	v_mfma_f32_16x16x32_bf16 v[60:63], v[158:161], v[232:235], v[60:63]
	s_mov_b32 m0, s10
	v_mfma_f32_16x16x32_bf16 v[44:47], v[158:161], v[236:239], v[44:47]
	global_load_lds_dwordx4 v[154:155], off
	v_lshl_add_u64 v[154:155], v[154:155], 0, 64
	v_mfma_f32_16x16x32_bf16 v[28:31], v[158:161], v[240:243], v[28:31]
	s_mov_b32 m0, s18
	v_mfma_f32_16x16x32_bf16 v[12:15], v[158:161], v[244:247], v[12:15]
	global_load_lds_dwordx4 v[152:153], off
	v_lshl_add_u64 v[152:153], v[152:153], 0, 64
	v_mfma_f32_16x16x32_bf16 v[56:59], v[162:165], v[232:235], v[56:59]
	ds_read_b128 v[158:161], v139
	s_mov_b32 m0, s11
	v_mfma_f32_16x16x32_bf16 v[40:43], v[162:165], v[236:239], v[40:43]
	global_load_lds_dwordx4 v[150:151], off
	v_lshl_add_u64 v[150:151], v[150:151], 0, 64
	v_mfma_f32_16x16x32_bf16 v[24:27], v[162:165], v[240:243], v[24:27]
	s_mov_b32 m0, s9
	v_mfma_f32_16x16x32_bf16 v[8:11], v[162:165], v[244:247], v[8:11]
	global_load_lds_dwordx4 v[148:149], off
	v_lshl_add_u64 v[148:149], v[148:149], 0, 64
	v_mfma_f32_16x16x32_bf16 v[52:55], v[166:169], v[232:235], v[52:55]
	ds_read_b128 v[162:165], v139 offset:1024
	v_mfma_f32_16x16x32_bf16 v[36:39], v[166:169], v[236:239], v[36:39]
	v_mfma_f32_16x16x32_bf16 v[20:23], v[166:169], v[240:243], v[20:23]
	v_mfma_f32_16x16x32_bf16 v[4:7], v[166:169], v[244:247], v[4:7]
	v_mfma_f32_16x16x32_bf16 v[48:51], v[182:185], v[232:235], v[48:51]
	ds_read_b128 v[166:169], v139 offset:2048
	v_mfma_f32_16x16x32_bf16 v[32:35], v[182:185], v[236:239], v[32:35]
	v_mfma_f32_16x16x32_bf16 v[16:19], v[182:185], v[240:243], v[16:19]
	v_mfma_f32_16x16x32_bf16 v[0:3], v[182:185], v[244:247], v[0:3]
	s_waitcnt lgkmcnt(2)
	v_mfma_f32_16x16x32_bf16 v[126:129], v[158:161], v[186:189], v[126:129]
	ds_read_b128 v[182:185], v139 offset:3072
	v_mfma_f32_16x16x32_bf16 v[108:111], v[158:161], v[190:193], v[108:111]
	ds_read_b128 v[232:235], v112 offset:4096
	ds_read_b128 v[236:239], v112 offset:5120
	v_mfma_f32_16x16x32_bf16 v[92:95], v[158:161], v[194:197], v[92:95]
	ds_read_b128 v[240:243], v112 offset:6144
	ds_read_b128 v[244:247], v112 offset:7168
	v_mfma_f32_16x16x32_bf16 v[76:79], v[158:161], v[198:201], v[76:79]
	s_waitcnt lgkmcnt(6)
	v_mfma_f32_16x16x32_bf16 v[122:125], v[162:165], v[186:189], v[122:125]
	v_mfma_f32_16x16x32_bf16 v[104:107], v[162:165], v[190:193], v[104:107]
	v_mfma_f32_16x16x32_bf16 v[88:91], v[162:165], v[194:197], v[88:91]
	v_mfma_f32_16x16x32_bf16 v[72:75], v[162:165], v[198:201], v[72:75]
	s_waitcnt lgkmcnt(5)
	v_mfma_f32_16x16x32_bf16 v[118:121], v[166:169], v[186:189], v[118:121]
	v_mfma_f32_16x16x32_bf16 v[100:103], v[166:169], v[190:193], v[100:103]
	v_mfma_f32_16x16x32_bf16 v[84:87], v[166:169], v[194:197], v[84:87]
	v_mfma_f32_16x16x32_bf16 v[68:71], v[166:169], v[198:201], v[68:71]
	s_waitcnt lgkmcnt(4)
	v_mfma_f32_16x16x32_bf16 v[114:117], v[182:185], v[186:189], v[114:117]
	v_mfma_f32_16x16x32_bf16 v[96:99], v[182:185], v[190:193], v[96:99]
	v_mfma_f32_16x16x32_bf16 v[80:83], v[182:185], v[194:197], v[80:83]
	v_mfma_f32_16x16x32_bf16 v[64:67], v[182:185], v[198:201], v[64:67]
	s_cbranch_scc0 .Lgsk0_loop
	s_waitcnt lgkmcnt(0)
	v_mfma_f32_16x16x32_bf16 v[60:63], v[158:161], v[232:235], v[60:63]
	v_mfma_f32_16x16x32_bf16 v[44:47], v[158:161], v[236:239], v[44:47]
	v_mfma_f32_16x16x32_bf16 v[28:31], v[158:161], v[240:243], v[28:31]
	v_mfma_f32_16x16x32_bf16 v[12:15], v[158:161], v[244:247], v[12:15]
	v_mfma_f32_16x16x32_bf16 v[56:59], v[162:165], v[232:235], v[56:59]
	v_mfma_f32_16x16x32_bf16 v[40:43], v[162:165], v[236:239], v[40:43]
	v_mfma_f32_16x16x32_bf16 v[24:27], v[162:165], v[240:243], v[24:27]
	v_mfma_f32_16x16x32_bf16 v[8:11], v[162:165], v[244:247], v[8:11]
	v_mfma_f32_16x16x32_bf16 v[52:55], v[166:169], v[232:235], v[52:55]
	v_mfma_f32_16x16x32_bf16 v[36:39], v[166:169], v[236:239], v[36:39]
	v_mfma_f32_16x16x32_bf16 v[20:23], v[166:169], v[240:243], v[20:23]
	v_mfma_f32_16x16x32_bf16 v[4:7], v[166:169], v[244:247], v[4:7]
	v_mfma_f32_16x16x32_bf16 v[48:51], v[182:185], v[232:235], v[48:51]
	v_mfma_f32_16x16x32_bf16 v[32:35], v[182:185], v[236:239], v[32:35]
	v_mfma_f32_16x16x32_bf16 v[16:19], v[182:185], v[240:243], v[16:19]
	v_mfma_f32_16x16x32_bf16 v[0:3], v[182:185], v[244:247], v[0:3]
	s_waitcnt vmcnt(8)
	s_barrier
	v_add_u32_e32 v112, 0x8000, v135
	v_or_b32_e32 v139, 0x8000, v137
	ds_read_b128 v[148:151], v139
	ds_read_b128 v[152:155], v139 offset:1024
	ds_read_b128 v[158:161], v139 offset:2048
	ds_read_b128 v[162:165], v139 offset:3072
	ds_read_b128 v[166:169], v112
	ds_read_b128 v[182:185], v112 offset:1024
	ds_read_b128 v[186:189], v112 offset:2048
	ds_read_b128 v[190:193], v112 offset:3072
	v_or_b32_e32 v139, 0x10000, v137
	s_waitcnt lgkmcnt(0)
	s_lshl_b32 s7, s4, 8
	v_mfma_f32_16x16x32_bf16 v[126:129], v[148:151], v[166:169], v[126:129]
	s_and_b32 s4, s4, 0xc0
	s_and_b32 s78, s7, 0xffffc000
	s_or_b32 s8, s5, s4
	v_mfma_f32_16x16x32_bf16 v[122:125], v[152:155], v[166:169], v[122:125]
	s_mov_b64 s[4:5], -1
	s_cmpk_gt_i32 s8, 0x17f
	v_mfma_f32_16x16x32_bf16 v[118:121], v[158:161], v[166:169], v[118:121]
	v_mfma_f32_16x16x32_bf16 v[114:117], v[162:165], v[166:169], v[114:117]
	v_mfma_f32_16x16x32_bf16 v[108:111], v[148:151], v[182:185], v[108:111]
	v_mfma_f32_16x16x32_bf16 v[104:107], v[152:155], v[182:185], v[104:107]
	v_mfma_f32_16x16x32_bf16 v[100:103], v[158:161], v[182:185], v[100:103]
	v_mfma_f32_16x16x32_bf16 v[96:99], v[162:165], v[182:185], v[96:99]
	v_mfma_f32_16x16x32_bf16 v[92:95], v[148:151], v[186:189], v[92:95]
	v_mfma_f32_16x16x32_bf16 v[88:91], v[152:155], v[186:189], v[88:91]
	v_mfma_f32_16x16x32_bf16 v[84:87], v[158:161], v[186:189], v[84:87]
	v_mfma_f32_16x16x32_bf16 v[80:83], v[162:165], v[186:189], v[80:83]
	v_mfma_f32_16x16x32_bf16 v[76:79], v[148:151], v[190:193], v[76:79]
	v_mfma_f32_16x16x32_bf16 v[72:75], v[152:155], v[190:193], v[72:75]
	v_mfma_f32_16x16x32_bf16 v[68:71], v[158:161], v[190:193], v[68:71]
	v_mfma_f32_16x16x32_bf16 v[64:67], v[162:165], v[190:193], v[64:67]
	ds_read_b128 v[166:169], v112 offset:4096
	ds_read_b128 v[182:185], v112 offset:5120
	ds_read_b128 v[186:189], v112 offset:6144
	ds_read_b128 v[190:193], v112 offset:7168
	s_waitcnt lgkmcnt(0)
	s_waitcnt vmcnt(4)
	s_barrier
	v_mfma_f32_16x16x32_bf16 v[60:63], v[148:151], v[166:169], v[60:63]
	v_add_u32_e32 v112, 0x10000, v135
	v_mfma_f32_16x16x32_bf16 v[56:59], v[152:155], v[166:169], v[56:59]
	v_mfma_f32_16x16x32_bf16 v[52:55], v[158:161], v[166:169], v[52:55]
	v_mfma_f32_16x16x32_bf16 v[48:51], v[162:165], v[166:169], v[48:51]
	v_mfma_f32_16x16x32_bf16 v[44:47], v[148:151], v[182:185], v[44:47]
	v_mfma_f32_16x16x32_bf16 v[40:43], v[152:155], v[182:185], v[40:43]
	v_mfma_f32_16x16x32_bf16 v[36:39], v[158:161], v[182:185], v[36:39]
	v_mfma_f32_16x16x32_bf16 v[32:35], v[162:165], v[182:185], v[32:35]
	v_mfma_f32_16x16x32_bf16 v[28:31], v[148:151], v[186:189], v[28:31]
	v_mfma_f32_16x16x32_bf16 v[24:27], v[152:155], v[186:189], v[24:27]
	v_mfma_f32_16x16x32_bf16 v[20:23], v[158:161], v[186:189], v[20:23]
	v_mfma_f32_16x16x32_bf16 v[16:19], v[162:165], v[186:189], v[16:19]
	v_mfma_f32_16x16x32_bf16 v[12:15], v[148:151], v[190:193], v[12:15]
	v_mfma_f32_16x16x32_bf16 v[8:11], v[152:155], v[190:193], v[8:11]
	v_mfma_f32_16x16x32_bf16 v[4:7], v[158:161], v[190:193], v[4:7]
	v_mfma_f32_16x16x32_bf16 v[0:3], v[162:165], v[190:193], v[0:3]
	ds_read_b128 v[148:151], v139
	ds_read_b128 v[152:155], v139 offset:1024
	ds_read_b128 v[158:161], v139 offset:2048
	ds_read_b128 v[162:165], v139 offset:3072
	ds_read_b128 v[166:169], v112
	ds_read_b128 v[182:185], v112 offset:1024
	ds_read_b128 v[186:189], v112 offset:2048
	ds_read_b128 v[190:193], v112 offset:3072
	s_nop 0
	s_waitcnt lgkmcnt(0)
	s_nop 0
	v_mfma_f32_16x16x32_bf16 v[126:129], v[148:151], v[166:169], v[126:129]
	v_mfma_f32_16x16x32_bf16 v[122:125], v[152:155], v[166:169], v[122:125]
	v_mfma_f32_16x16x32_bf16 v[118:121], v[158:161], v[166:169], v[118:121]
	v_mfma_f32_16x16x32_bf16 v[114:117], v[162:165], v[166:169], v[114:117]
	v_mfma_f32_16x16x32_bf16 v[108:111], v[148:151], v[182:185], v[108:111]
	v_mfma_f32_16x16x32_bf16 v[104:107], v[152:155], v[182:185], v[104:107]
	v_mfma_f32_16x16x32_bf16 v[100:103], v[158:161], v[182:185], v[100:103]
	v_mfma_f32_16x16x32_bf16 v[96:99], v[162:165], v[182:185], v[96:99]
	v_mfma_f32_16x16x32_bf16 v[92:95], v[148:151], v[186:189], v[92:95]
	v_mfma_f32_16x16x32_bf16 v[88:91], v[152:155], v[186:189], v[88:91]
	v_mfma_f32_16x16x32_bf16 v[84:87], v[158:161], v[186:189], v[84:87]
	v_mfma_f32_16x16x32_bf16 v[80:83], v[162:165], v[186:189], v[80:83]
	v_mfma_f32_16x16x32_bf16 v[76:79], v[148:151], v[190:193], v[76:79]
	v_mfma_f32_16x16x32_bf16 v[72:75], v[152:155], v[190:193], v[72:75]
	v_mfma_f32_16x16x32_bf16 v[68:71], v[158:161], v[190:193], v[68:71]
	v_mfma_f32_16x16x32_bf16 v[64:67], v[162:165], v[190:193], v[64:67]
	ds_read_b128 v[166:169], v112 offset:4096
	ds_read_b128 v[182:185], v112 offset:5120
	ds_read_b128 v[186:189], v112 offset:6144
	ds_read_b128 v[190:193], v112 offset:7168
	s_waitcnt lgkmcnt(0)
	s_waitcnt vmcnt(0)
	s_barrier
	v_mfma_f32_16x16x32_bf16 v[60:63], v[148:151], v[166:169], v[60:63]
	v_add_u32_e32 v112, 0x18000, v135
	v_or_b32_e32 v135, 0x18000, v137
	v_mfma_f32_16x16x32_bf16 v[56:59], v[152:155], v[166:169], v[56:59]
	v_bfe_u32 v137, v131, 4, 2
	v_mfma_f32_16x16x32_bf16 v[52:55], v[158:161], v[166:169], v[52:55]
	v_mfma_f32_16x16x32_bf16 v[48:51], v[162:165], v[166:169], v[48:51]
	v_mfma_f32_16x16x32_bf16 v[44:47], v[148:151], v[182:185], v[44:47]
	v_mfma_f32_16x16x32_bf16 v[40:43], v[152:155], v[182:185], v[40:43]
	v_mfma_f32_16x16x32_bf16 v[36:39], v[158:161], v[182:185], v[36:39]
	v_mfma_f32_16x16x32_bf16 v[32:35], v[162:165], v[182:185], v[32:35]
	v_mfma_f32_16x16x32_bf16 v[28:31], v[148:151], v[186:189], v[28:31]
	v_mfma_f32_16x16x32_bf16 v[24:27], v[152:155], v[186:189], v[24:27]
	v_mfma_f32_16x16x32_bf16 v[20:23], v[158:161], v[186:189], v[20:23]
	v_mfma_f32_16x16x32_bf16 v[16:19], v[162:165], v[186:189], v[16:19]
	v_mfma_f32_16x16x32_bf16 v[12:15], v[148:151], v[190:193], v[12:15]
	v_mfma_f32_16x16x32_bf16 v[8:11], v[152:155], v[190:193], v[8:11]
	v_mfma_f32_16x16x32_bf16 v[4:7], v[158:161], v[190:193], v[4:7]
	v_mfma_f32_16x16x32_bf16 v[0:3], v[162:165], v[190:193], v[0:3]
	ds_read_b128 v[164:167], v135
	ds_read_b128 v[168:171], v135 offset:1024
	ds_read_b128 v[182:185], v135 offset:2048
	ds_read_b128 v[186:189], v135 offset:3072
	ds_read_b128 v[148:151], v112
	ds_read_b128 v[152:155], v112 offset:1024
	ds_read_b128 v[158:161], v112 offset:2048
	ds_read_b128 v[190:193], v112 offset:3072
	v_or_b32_e32 v162, 16, v144
	s_waitcnt lgkmcnt(0)
	v_ashrrev_i32_e32 v163, 31, v162
	v_mfma_f32_16x16x32_bf16 v[126:129], v[164:167], v[148:151], v[126:129]
	v_and_b32_e32 v135, 63, v131
	v_mfma_f32_16x16x32_bf16 v[122:125], v[168:171], v[148:151], v[122:125]
	v_mfma_f32_16x16x32_bf16 v[118:121], v[182:185], v[148:151], v[118:121]
	v_mfma_f32_16x16x32_bf16 v[114:117], v[186:189], v[148:151], v[114:117]
	v_mfma_f32_16x16x32_bf16 v[108:111], v[164:167], v[152:155], v[108:111]
	v_mfma_f32_16x16x32_bf16 v[104:107], v[168:171], v[152:155], v[104:107]
	v_mfma_f32_16x16x32_bf16 v[100:103], v[182:185], v[152:155], v[100:103]
	v_mfma_f32_16x16x32_bf16 v[96:99], v[186:189], v[152:155], v[96:99]
	v_mfma_f32_16x16x32_bf16 v[92:95], v[164:167], v[158:161], v[92:95]
	v_mfma_f32_16x16x32_bf16 v[88:91], v[168:171], v[158:161], v[88:91]
	v_mfma_f32_16x16x32_bf16 v[84:87], v[182:185], v[158:161], v[84:87]
	v_mfma_f32_16x16x32_bf16 v[80:83], v[186:189], v[158:161], v[80:83]
	v_or_b32_e32 v160, 32, v144
	v_or_b32_e32 v158, 48, v144
	v_ashrrev_i32_e32 v161, 31, v160
	v_mfma_f32_16x16x32_bf16 v[76:79], v[164:167], v[190:193], v[76:79]
	v_ashrrev_i32_e32 v159, 31, v158
	v_mfma_f32_16x16x32_bf16 v[72:75], v[168:171], v[190:193], v[72:75]
	v_mfma_f32_16x16x32_bf16 v[68:71], v[182:185], v[190:193], v[68:71]
	v_mfma_f32_16x16x32_bf16 v[64:67], v[186:189], v[190:193], v[64:67]
	ds_read_b128 v[148:151], v112 offset:4096
	ds_read_b128 v[152:155], v112 offset:5120
	ds_read_b128 v[190:193], v112 offset:6144
	ds_read_b128 v[194:197], v112 offset:7168
	s_waitcnt lgkmcnt(0)
	s_barrier
	v_mfma_f32_16x16x32_bf16 v[60:63], v[164:167], v[148:151], v[60:63]
	v_mfma_f32_16x16x32_bf16 v[56:59], v[168:171], v[148:151], v[56:59]
	v_mfma_f32_16x16x32_bf16 v[52:55], v[182:185], v[148:151], v[52:55]
	v_mfma_f32_16x16x32_bf16 v[48:51], v[186:189], v[148:151], v[48:51]
	v_or_b32_e32 v150, 0x60, v144
	v_or_b32_e32 v148, 0x70, v144
	v_ashrrev_i32_e32 v151, 31, v150
	v_mfma_f32_16x16x32_bf16 v[44:47], v[164:167], v[152:155], v[44:47]
	v_ashrrev_i32_e32 v149, 31, v148
	v_mfma_f32_16x16x32_bf16 v[40:43], v[168:171], v[152:155], v[40:43]
	v_mfma_f32_16x16x32_bf16 v[36:39], v[182:185], v[152:155], v[36:39]
	v_mfma_f32_16x16x32_bf16 v[32:35], v[186:189], v[152:155], v[32:35]
	v_or_b32_e32 v154, 64, v144
	v_or_b32_e32 v152, 0x50, v144
	v_ashrrev_i32_e32 v155, 31, v154
	v_mfma_f32_16x16x32_bf16 v[28:31], v[164:167], v[190:193], v[28:31]
	v_ashrrev_i32_e32 v153, 31, v152
	v_mfma_f32_16x16x32_bf16 v[24:27], v[168:171], v[190:193], v[24:27]
	v_mfma_f32_16x16x32_bf16 v[20:23], v[182:185], v[190:193], v[20:23]
	v_mfma_f32_16x16x32_bf16 v[16:19], v[186:189], v[190:193], v[16:19]
	v_mfma_f32_16x16x32_bf16 v[12:15], v[164:167], v[194:197], v[12:15]
	v_mfma_f32_16x16x32_bf16 v[8:11], v[168:171], v[194:197], v[8:11]
	v_mfma_f32_16x16x32_bf16 v[4:7], v[182:185], v[194:197], v[4:7]
	v_mfma_f32_16x16x32_bf16 v[0:3], v[186:189], v[194:197], v[0:3]
	s_cbranch_scc0 .LBB0_213
	s_cmpk_gt_u32 s8, 0x57f
	s_cbranch_scc0 .LBB0_210
	s_cmpk_lg_i32 s8, 0x580
	s_cbranch_scc1 .LBB0_209
	v_lshlrev_b32_e32 v112, 7, v144
	v_and_b32_e32 v112, 0x7c780, v112
	v_lshl_add_u64 v[164:165], s[46:47], 0, v[112:113]
	v_lshlrev_b32_e32 v112, 5, v137
	v_lshl_add_u64 v[168:169], v[164:165], 0, v[112:113]
	global_load_dwordx4 v[164:167], v[168:169], off offset:16
	s_nop 0
	global_load_dwordx4 v[168:171], v[168:169], off
	v_pk_mul_f32 v[184:185], v[146:147], v[122:123] op_sel_hi:[0,1]
	v_pk_mul_f32 v[176:177], v[146:147], v[126:127] op_sel_hi:[0,1]
	v_pk_mul_f32 v[182:183], v[146:147], v[124:125] op_sel_hi:[0,1]
	v_pk_mul_f32 v[174:175], v[146:147], v[128:129] op_sel_hi:[0,1]
	v_lshlrev_b32_e32 v139, 7, v162
	s_waitcnt vmcnt(0)
	v_mov_b32_e32 v186, v168
	v_mov_b32_e32 v187, v170
	v_mov_b32_e32 v170, v169
	v_pk_mul_f32 v[168:169], v[184:185], v[170:171]
	v_pk_mul_f32 v[184:185], v[184:185], v[186:187]
	v_pk_fma_f32 v[168:169], v[176:177], v[186:187], v[168:169] neg_lo:[0,0,1] neg_hi:[0,0,1]
	v_pk_fma_f32 v[170:171], v[176:177], v[170:171], v[184:185]
	v_mov_b32_e32 v177, v166
	v_mov_b32_e32 v166, v165
	v_mov_b32_e32 v176, v164
	v_pk_mul_f32 v[164:165], v[182:183], v[166:167]
	v_cvt_pk_bf16_f32 v168, v168, v169
	v_pk_fma_f32 v[164:165], v[174:175], v[176:177], v[164:165] neg_lo:[0,0,1] neg_hi:[0,0,1]
	v_pk_mul_f32 v[176:177], v[182:183], v[176:177]
	v_cvt_pk_bf16_f32 v169, v164, v165
	v_lshlrev_b64 v[164:165], 6, v[144:145]
	v_pk_fma_f32 v[166:167], v[174:175], v[166:167], v[176:177]
	v_lshl_add_u64 v[174:175], s[36:37], 0, v[164:165]
	v_lshlrev_b32_e32 v164, 3, v137
	v_mov_b32_e32 v165, v113
	v_lshl_add_u64 v[174:175], v[174:175], 0, v[164:165]
	global_store_dwordx2 v[174:175], v[168:169], off
	v_cvt_pk_bf16_f32 v169, v166, v167
	v_and_b32_e32 v166, 0x7cf80, v139
	v_mov_b32_e32 v167, v113
	v_cvt_pk_bf16_f32 v168, v170, v171
	v_lshl_add_u64 v[166:167], s[46:47], 0, v[166:167]
	global_store_dwordx2 v[174:175], v[168:169], off offset:32
	v_lshl_add_u64 v[182:183], v[166:167], 0, v[112:113]
	global_load_dwordx4 v[166:169], v[182:183], off offset:16
	s_nop 0
	global_load_dwordx4 v[182:185], v[182:183], off
	v_pk_mul_f32 v[186:187], v[142:143], v[104:105] op_sel_hi:[0,1]
	v_pk_mul_f32 v[174:175], v[142:143], v[108:109] op_sel_hi:[0,1]
	v_pk_mul_f32 v[176:177], v[142:143], v[106:107] op_sel_hi:[0,1]
	v_pk_mul_f32 v[170:171], v[142:143], v[110:111] op_sel_hi:[0,1]
	v_lshlrev_b32_e32 v139, 7, v160
	s_waitcnt vmcnt(0)
	v_mov_b32_e32 v188, v182
	v_mov_b32_e32 v189, v184
	v_mov_b32_e32 v184, v183
	v_pk_mul_f32 v[182:183], v[186:187], v[184:185]
	v_pk_mul_f32 v[186:187], v[186:187], v[188:189]
	v_pk_fma_f32 v[182:183], v[174:175], v[188:189], v[182:183] neg_lo:[0,0,1] neg_hi:[0,0,1]
	v_pk_fma_f32 v[174:175], v[174:175], v[184:185], v[186:187]
	v_mov_b32_e32 v185, v168
	v_mov_b32_e32 v168, v167
	v_mov_b32_e32 v184, v166
	v_pk_mul_f32 v[166:167], v[176:177], v[168:169]
	v_pk_mul_f32 v[176:177], v[176:177], v[184:185]
	v_pk_fma_f32 v[166:167], v[170:171], v[184:185], v[166:167] neg_lo:[0,0,1] neg_hi:[0,0,1]
	v_pk_fma_f32 v[168:169], v[170:171], v[168:169], v[176:177]
	v_cvt_pk_bf16_f32 v171, v166, v167
	v_lshlrev_b64 v[166:167], 6, v[162:163]
	v_lshl_add_u64 v[166:167], s[36:37], 0, v[166:167]
	v_cvt_pk_bf16_f32 v170, v182, v183
	v_lshl_add_u64 v[166:167], v[166:167], 0, v[164:165]
	global_store_dwordx2 v[166:167], v[170:171], off
	v_cvt_pk_bf16_f32 v170, v174, v175
	v_cvt_pk_bf16_f32 v171, v168, v169
	global_store_dwordx2 v[166:167], v[170:171], off offset:32
	v_and_b32_e32 v166, 0x7d780, v139
	v_mov_b32_e32 v167, v113
	v_lshl_add_u64 v[166:167], s[46:47], 0, v[166:167]
	v_lshl_add_u64 v[182:183], v[166:167], 0, v[112:113]
	global_load_dwordx4 v[166:169], v[182:183], off offset:16
	s_nop 0
	global_load_dwordx4 v[182:185], v[182:183], off
	v_pk_mul_f32 v[186:187], v[140:141], v[88:89] op_sel_hi:[0,1]
	v_pk_mul_f32 v[174:175], v[140:141], v[92:93] op_sel_hi:[0,1]
	v_pk_mul_f32 v[176:177], v[140:141], v[90:91] op_sel_hi:[0,1]
	v_pk_mul_f32 v[170:171], v[140:141], v[94:95] op_sel_hi:[0,1]
	s_waitcnt vmcnt(0)
	v_mov_b32_e32 v188, v182
	v_mov_b32_e32 v189, v184
	v_mov_b32_e32 v184, v183
	v_pk_mul_f32 v[182:183], v[186:187], v[184:185]
	v_pk_mul_f32 v[186:187], v[186:187], v[188:189]
	v_pk_fma_f32 v[182:183], v[174:175], v[188:189], v[182:183] neg_lo:[0,0,1] neg_hi:[0,0,1]
	v_pk_fma_f32 v[174:175], v[174:175], v[184:185], v[186:187]
	v_mov_b32_e32 v185, v168
	v_mov_b32_e32 v168, v167
	v_mov_b32_e32 v184, v166
	v_pk_mul_f32 v[166:167], v[176:177], v[168:169]
	v_pk_mul_f32 v[176:177], v[176:177], v[184:185]
	v_pk_fma_f32 v[166:167], v[170:171], v[184:185], v[166:167] neg_lo:[0,0,1] neg_hi:[0,0,1]
	v_pk_fma_f32 v[168:169], v[170:171], v[168:169], v[176:177]
	v_cvt_pk_bf16_f32 v171, v166, v167
	v_lshlrev_b64 v[166:167], 6, v[160:161]
	v_lshl_add_u64 v[166:167], s[36:37], 0, v[166:167]
	v_cvt_pk_bf16_f32 v170, v182, v183
	v_lshl_add_u64 v[166:167], v[166:167], 0, v[164:165]
	global_store_dwordx2 v[166:167], v[170:171], off
	v_cvt_pk_bf16_f32 v170, v174, v175
	v_cvt_pk_bf16_f32 v171, v168, v169
	global_store_dwordx2 v[166:167], v[170:171], off offset:32
	v_pk_mul_f32 v[170:171], v[138:139], v[78:79] op_sel_hi:[0,1]
	v_pk_mul_f32 v[174:175], v[138:139], v[76:77] op_sel_hi:[0,1]
	v_pk_mul_f32 v[176:177], v[138:139], v[74:75] op_sel_hi:[0,1]
	v_pk_mul_f32 v[186:187], v[138:139], v[72:73] op_sel_hi:[0,1]
	v_lshlrev_b32_e32 v139, 7, v158
	v_and_b32_e32 v166, 0x7df80, v139
	v_mov_b32_e32 v167, v113
	v_lshl_add_u64 v[166:167], s[46:47], 0, v[166:167]
	v_lshl_add_u64 v[182:183], v[166:167], 0, v[112:113]
	global_load_dwordx4 v[166:169], v[182:183], off offset:16
	s_nop 0
	global_load_dwordx4 v[182:185], v[182:183], off
	v_lshlrev_b32_e32 v139, 7, v154
	s_waitcnt vmcnt(0)
	v_mov_b32_e32 v188, v182
	v_mov_b32_e32 v189, v184
	v_mov_b32_e32 v184, v183
	v_pk_mul_f32 v[182:183], v[186:187], v[184:185]
	v_pk_mul_f32 v[186:187], v[186:187], v[188:189]
	v_pk_fma_f32 v[182:183], v[174:175], v[188:189], v[182:183] neg_lo:[0,0,1] neg_hi:[0,0,1]
	v_pk_fma_f32 v[174:175], v[174:175], v[184:185], v[186:187]
	v_mov_b32_e32 v185, v168
	v_mov_b32_e32 v168, v167
	v_mov_b32_e32 v184, v166
	v_pk_mul_f32 v[166:167], v[176:177], v[168:169]
	v_pk_mul_f32 v[176:177], v[176:177], v[184:185]
	v_pk_fma_f32 v[166:167], v[170:171], v[184:185], v[166:167] neg_lo:[0,0,1] neg_hi:[0,0,1]
	v_pk_fma_f32 v[168:169], v[170:171], v[168:169], v[176:177]
	v_cvt_pk_bf16_f32 v171, v166, v167
	v_lshlrev_b64 v[166:167], 6, v[158:159]
	v_lshl_add_u64 v[166:167], s[36:37], 0, v[166:167]
	v_cvt_pk_bf16_f32 v170, v182, v183
	v_lshl_add_u64 v[166:167], v[166:167], 0, v[164:165]
	global_store_dwordx2 v[166:167], v[170:171], off
	v_cvt_pk_bf16_f32 v170, v174, v175
	v_cvt_pk_bf16_f32 v171, v168, v169
	global_store_dwordx2 v[166:167], v[170:171], off offset:32
	v_and_b32_e32 v166, 0x7e780, v139
	v_mov_b32_e32 v167, v113
	v_lshl_add_u64 v[166:167], s[46:47], 0, v[166:167]
	v_lshl_add_u64 v[182:183], v[166:167], 0, v[112:113]
	global_load_dwordx4 v[166:169], v[182:183], off offset:16
	s_nop 0
	global_load_dwordx4 v[182:185], v[182:183], off
	v_pk_mul_f32 v[186:187], v[136:137], v[56:57] op_sel_hi:[0,1]
	v_pk_mul_f32 v[174:175], v[136:137], v[60:61] op_sel_hi:[0,1]
	v_pk_mul_f32 v[176:177], v[136:137], v[58:59] op_sel_hi:[0,1]
	v_pk_mul_f32 v[170:171], v[136:137], v[62:63] op_sel_hi:[0,1]
	v_lshlrev_b32_e32 v139, 7, v152
	s_waitcnt vmcnt(0)
	v_mov_b32_e32 v188, v182
	v_mov_b32_e32 v189, v184
	v_mov_b32_e32 v184, v183
	v_pk_mul_f32 v[182:183], v[186:187], v[184:185]
	v_pk_mul_f32 v[186:187], v[186:187], v[188:189]
	v_pk_fma_f32 v[182:183], v[174:175], v[188:189], v[182:183] neg_lo:[0,0,1] neg_hi:[0,0,1]
	v_pk_fma_f32 v[174:175], v[174:175], v[184:185], v[186:187]
	v_mov_b32_e32 v185, v168
	v_mov_b32_e32 v168, v167
	v_mov_b32_e32 v184, v166
	v_pk_mul_f32 v[166:167], v[176:177], v[168:169]
	v_pk_mul_f32 v[176:177], v[176:177], v[184:185]
	v_pk_fma_f32 v[166:167], v[170:171], v[184:185], v[166:167] neg_lo:[0,0,1] neg_hi:[0,0,1]
	v_pk_fma_f32 v[168:169], v[170:171], v[168:169], v[176:177]
	v_cvt_pk_bf16_f32 v171, v166, v167
	v_lshlrev_b64 v[166:167], 6, v[154:155]
	v_lshl_add_u64 v[166:167], s[36:37], 0, v[166:167]
	v_cvt_pk_bf16_f32 v170, v182, v183
	v_lshl_add_u64 v[166:167], v[166:167], 0, v[164:165]
	global_store_dwordx2 v[166:167], v[170:171], off
	v_cvt_pk_bf16_f32 v170, v174, v175
	v_cvt_pk_bf16_f32 v171, v168, v169
	global_store_dwordx2 v[166:167], v[170:171], off offset:32
	v_and_b32_e32 v166, 0x7ef80, v139
	v_mov_b32_e32 v167, v113
	v_lshl_add_u64 v[166:167], s[46:47], 0, v[166:167]
	v_lshl_add_u64 v[182:183], v[166:167], 0, v[112:113]
	global_load_dwordx4 v[166:169], v[182:183], off offset:16
	s_nop 0
	global_load_dwordx4 v[182:185], v[182:183], off
	v_pk_mul_f32 v[186:187], v[134:135], v[40:41] op_sel_hi:[0,1]
	v_pk_mul_f32 v[174:175], v[134:135], v[44:45] op_sel_hi:[0,1]
	v_pk_mul_f32 v[176:177], v[134:135], v[42:43] op_sel_hi:[0,1]
	v_pk_mul_f32 v[170:171], v[134:135], v[46:47] op_sel_hi:[0,1]
	v_lshlrev_b32_e32 v139, 7, v150
	s_waitcnt vmcnt(0)
	v_mov_b32_e32 v188, v182
	v_mov_b32_e32 v189, v184
	v_mov_b32_e32 v184, v183
	v_pk_mul_f32 v[182:183], v[186:187], v[184:185]
	v_pk_mul_f32 v[186:187], v[186:187], v[188:189]
	v_pk_fma_f32 v[182:183], v[174:175], v[188:189], v[182:183] neg_lo:[0,0,1] neg_hi:[0,0,1]
	v_pk_fma_f32 v[174:175], v[174:175], v[184:185], v[186:187]
	v_mov_b32_e32 v185, v168
	v_mov_b32_e32 v168, v167
	v_mov_b32_e32 v184, v166
	v_pk_mul_f32 v[166:167], v[176:177], v[168:169]
	v_pk_mul_f32 v[176:177], v[176:177], v[184:185]
	v_pk_fma_f32 v[166:167], v[170:171], v[184:185], v[166:167] neg_lo:[0,0,1] neg_hi:[0,0,1]
	v_pk_fma_f32 v[168:169], v[170:171], v[168:169], v[176:177]
	v_cvt_pk_bf16_f32 v171, v166, v167
	v_lshlrev_b64 v[166:167], 6, v[152:153]
	v_lshl_add_u64 v[166:167], s[36:37], 0, v[166:167]
	v_cvt_pk_bf16_f32 v170, v182, v183
	v_lshl_add_u64 v[166:167], v[166:167], 0, v[164:165]
	global_store_dwordx2 v[166:167], v[170:171], off
	v_cvt_pk_bf16_f32 v170, v174, v175
	v_cvt_pk_bf16_f32 v171, v168, v169
	global_store_dwordx2 v[166:167], v[170:171], off offset:32
	v_and_b32_e32 v166, 0x7f780, v139
	v_mov_b32_e32 v167, v113
	v_lshl_add_u64 v[166:167], s[46:47], 0, v[166:167]
	v_lshl_add_u64 v[182:183], v[166:167], 0, v[112:113]
	global_load_dwordx4 v[166:169], v[182:183], off offset:16
	s_nop 0
	global_load_dwordx4 v[182:185], v[182:183], off
	v_pk_mul_f32 v[186:187], v[132:133], v[24:25] op_sel_hi:[0,1]
	v_pk_mul_f32 v[174:175], v[132:133], v[28:29] op_sel_hi:[0,1]
	v_pk_mul_f32 v[176:177], v[132:133], v[26:27] op_sel_hi:[0,1]
	v_pk_mul_f32 v[170:171], v[132:133], v[30:31] op_sel_hi:[0,1]
	v_lshlrev_b32_e32 v139, 7, v148
	s_waitcnt vmcnt(0)
	v_mov_b32_e32 v188, v182
	v_mov_b32_e32 v189, v184
	v_mov_b32_e32 v184, v183
	v_pk_mul_f32 v[182:183], v[186:187], v[184:185]
	v_pk_mul_f32 v[186:187], v[186:187], v[188:189]
	v_pk_fma_f32 v[182:183], v[174:175], v[188:189], v[182:183] neg_lo:[0,0,1] neg_hi:[0,0,1]
	v_pk_fma_f32 v[174:175], v[174:175], v[184:185], v[186:187]
	v_mov_b32_e32 v185, v168
	v_mov_b32_e32 v168, v167
	v_mov_b32_e32 v184, v166
	v_pk_mul_f32 v[166:167], v[176:177], v[168:169]
	v_pk_mul_f32 v[176:177], v[176:177], v[184:185]
	v_pk_fma_f32 v[166:167], v[170:171], v[184:185], v[166:167] neg_lo:[0,0,1] neg_hi:[0,0,1]
	v_pk_fma_f32 v[168:169], v[170:171], v[168:169], v[176:177]
	v_cvt_pk_bf16_f32 v171, v166, v167
	v_lshlrev_b64 v[166:167], 6, v[150:151]
	v_lshl_add_u64 v[166:167], s[36:37], 0, v[166:167]
	v_cvt_pk_bf16_f32 v170, v182, v183
	v_lshl_add_u64 v[166:167], v[166:167], 0, v[164:165]
	global_store_dwordx2 v[166:167], v[170:171], off
	v_cvt_pk_bf16_f32 v170, v174, v175
	v_cvt_pk_bf16_f32 v171, v168, v169
	global_store_dwordx2 v[166:167], v[170:171], off offset:32
	v_and_b32_e32 v166, 0x7ff80, v139
	v_mov_b32_e32 v167, v113
	v_lshl_add_u64 v[166:167], s[46:47], 0, v[166:167]
	v_lshl_add_u64 v[182:183], v[166:167], 0, v[112:113]
	global_load_dwordx4 v[166:169], v[182:183], off offset:16
	s_nop 0
	global_load_dwordx4 v[182:185], v[182:183], off
	v_pk_mul_f32 v[186:187], v[130:131], v[8:9] op_sel_hi:[0,1]
	v_pk_mul_f32 v[174:175], v[130:131], v[12:13] op_sel_hi:[0,1]
	v_pk_mul_f32 v[176:177], v[130:131], v[10:11] op_sel_hi:[0,1]
	v_pk_mul_f32 v[170:171], v[130:131], v[14:15] op_sel_hi:[0,1]
	s_waitcnt vmcnt(0)
	v_mov_b32_e32 v188, v182
	v_mov_b32_e32 v189, v184
	v_mov_b32_e32 v184, v183
	v_pk_mul_f32 v[182:183], v[186:187], v[184:185]
	v_pk_mul_f32 v[186:187], v[186:187], v[188:189]
	v_pk_fma_f32 v[182:183], v[174:175], v[188:189], v[182:183] neg_lo:[0,0,1] neg_hi:[0,0,1]
	v_pk_fma_f32 v[174:175], v[174:175], v[184:185], v[186:187]
	v_mov_b32_e32 v185, v168
	v_mov_b32_e32 v168, v167
	v_mov_b32_e32 v184, v166
	v_pk_mul_f32 v[166:167], v[176:177], v[168:169]
	v_pk_mul_f32 v[176:177], v[176:177], v[184:185]
	v_pk_fma_f32 v[166:167], v[170:171], v[184:185], v[166:167] neg_lo:[0,0,1] neg_hi:[0,0,1]
	v_pk_fma_f32 v[168:169], v[170:171], v[168:169], v[176:177]
	v_cvt_pk_bf16_f32 v171, v166, v167
	v_lshlrev_b64 v[166:167], 6, v[148:149]
	v_lshl_add_u64 v[166:167], s[36:37], 0, v[166:167]
	v_cvt_pk_bf16_f32 v170, v182, v183
	v_lshl_add_u64 v[164:165], v[166:167], 0, v[164:165]
	v_cvt_pk_bf16_f32 v166, v174, v175
	v_cvt_pk_bf16_f32 v167, v168, v169
	global_store_dwordx2 v[164:165], v[170:171], off
	global_store_dwordx2 v[164:165], v[166:167], off offset:32

.Lgsk1_loop:
	s_add_i32 s9, s8, 0xfffe8000
	s_and_b32 s10, s8, 0x18000
	s_waitcnt vmcnt(8) lgkmcnt(0)
	s_barrier
	s_and_b32 s9, s9, 0x18000
	s_add_i32 s10, s7, s10
	v_add_u32_e32 v112, s9, v139
	v_or_b32_e32 v141, s9, v140
	s_add_i32 s18, s10, 0x400
	s_add_i32 s11, s10, 0x800
	s_add_i32 s9, s10, 0xc00
	s_add_i32 s8, s8, 0x8000
	s_cmp_eq_u32 s8, 0x100000
	ds_read_b128 v[162:165], v112
	ds_read_b128 v[166:169], v112 offset:1024
	ds_read_b128 v[174:177], v112 offset:2048
	ds_read_b128 v[182:185], v112 offset:3072
	v_mfma_f32_16x16x32_bf16 v[60:63], v[142:145], v[232:235], v[60:63]
	s_mov_b32 m0, s10
	v_mfma_f32_16x16x32_bf16 v[44:47], v[142:145], v[236:239], v[44:47]
	global_load_lds_dwordx4 v[136:137], off
	v_lshl_add_u64 v[136:137], v[136:137], 0, 64
	v_mfma_f32_16x16x32_bf16 v[28:31], v[142:145], v[240:243], v[28:31]
	s_mov_b32 m0, s18
	v_mfma_f32_16x16x32_bf16 v[12:15], v[142:145], v[244:247], v[12:15]
	global_load_lds_dwordx4 v[134:135], off
	v_lshl_add_u64 v[134:135], v[134:135], 0, 64
	v_mfma_f32_16x16x32_bf16 v[56:59], v[146:149], v[232:235], v[56:59]
	ds_read_b128 v[142:145], v141
	s_mov_b32 m0, s11
	v_mfma_f32_16x16x32_bf16 v[40:43], v[146:149], v[236:239], v[40:43]
	global_load_lds_dwordx4 v[132:133], off
	v_lshl_add_u64 v[132:133], v[132:133], 0, 64
	v_mfma_f32_16x16x32_bf16 v[24:27], v[146:149], v[240:243], v[24:27]
	s_mov_b32 m0, s9
	v_mfma_f32_16x16x32_bf16 v[8:11], v[146:149], v[244:247], v[8:11]
	global_load_lds_dwordx4 v[130:131], off
	v_lshl_add_u64 v[130:131], v[130:131], 0, 64
	v_mfma_f32_16x16x32_bf16 v[52:55], v[150:153], v[232:235], v[52:55]
	ds_read_b128 v[146:149], v141 offset:1024
	v_mfma_f32_16x16x32_bf16 v[36:39], v[150:153], v[236:239], v[36:39]
	v_mfma_f32_16x16x32_bf16 v[20:23], v[150:153], v[240:243], v[20:23]
	v_mfma_f32_16x16x32_bf16 v[4:7], v[150:153], v[244:247], v[4:7]
	v_mfma_f32_16x16x32_bf16 v[48:51], v[158:161], v[232:235], v[48:51]
	ds_read_b128 v[150:153], v141 offset:2048
	v_mfma_f32_16x16x32_bf16 v[32:35], v[158:161], v[236:239], v[32:35]
	v_mfma_f32_16x16x32_bf16 v[16:19], v[158:161], v[240:243], v[16:19]
	v_mfma_f32_16x16x32_bf16 v[0:3], v[158:161], v[244:247], v[0:3]
	s_waitcnt lgkmcnt(2)
	v_mfma_f32_16x16x32_bf16 v[126:129], v[142:145], v[162:165], v[126:129]
	ds_read_b128 v[158:161], v141 offset:3072
	v_mfma_f32_16x16x32_bf16 v[108:111], v[142:145], v[166:169], v[108:111]
	ds_read_b128 v[232:235], v112 offset:4096
	ds_read_b128 v[236:239], v112 offset:5120
	v_mfma_f32_16x16x32_bf16 v[92:95], v[142:145], v[174:177], v[92:95]
	ds_read_b128 v[240:243], v112 offset:6144
	ds_read_b128 v[244:247], v112 offset:7168
	v_mfma_f32_16x16x32_bf16 v[76:79], v[142:145], v[182:185], v[76:79]
	s_waitcnt lgkmcnt(6)
	v_mfma_f32_16x16x32_bf16 v[122:125], v[146:149], v[162:165], v[122:125]
	v_mfma_f32_16x16x32_bf16 v[104:107], v[146:149], v[166:169], v[104:107]
	v_mfma_f32_16x16x32_bf16 v[88:91], v[146:149], v[174:177], v[88:91]
	v_mfma_f32_16x16x32_bf16 v[72:75], v[146:149], v[182:185], v[72:75]
	s_waitcnt lgkmcnt(5)
	v_mfma_f32_16x16x32_bf16 v[118:121], v[150:153], v[162:165], v[118:121]
	v_mfma_f32_16x16x32_bf16 v[100:103], v[150:153], v[166:169], v[100:103]
	v_mfma_f32_16x16x32_bf16 v[84:87], v[150:153], v[174:177], v[84:87]
	v_mfma_f32_16x16x32_bf16 v[68:71], v[150:153], v[182:185], v[68:71]
	s_waitcnt lgkmcnt(4)
	v_mfma_f32_16x16x32_bf16 v[114:117], v[158:161], v[162:165], v[114:117]
	v_mfma_f32_16x16x32_bf16 v[96:99], v[158:161], v[166:169], v[96:99]
	v_mfma_f32_16x16x32_bf16 v[80:83], v[158:161], v[174:177], v[80:83]
	v_mfma_f32_16x16x32_bf16 v[64:67], v[158:161], v[182:185], v[64:67]
	s_cbranch_scc0 .Lgsk1_loop
	s_waitcnt lgkmcnt(0)
	v_mfma_f32_16x16x32_bf16 v[60:63], v[142:145], v[232:235], v[60:63]
	v_mfma_f32_16x16x32_bf16 v[44:47], v[142:145], v[236:239], v[44:47]
	v_mfma_f32_16x16x32_bf16 v[28:31], v[142:145], v[240:243], v[28:31]
	v_mfma_f32_16x16x32_bf16 v[12:15], v[142:145], v[244:247], v[12:15]
	v_mfma_f32_16x16x32_bf16 v[56:59], v[146:149], v[232:235], v[56:59]
	v_mfma_f32_16x16x32_bf16 v[40:43], v[146:149], v[236:239], v[40:43]
	v_mfma_f32_16x16x32_bf16 v[24:27], v[146:149], v[240:243], v[24:27]
	v_mfma_f32_16x16x32_bf16 v[8:11], v[146:149], v[244:247], v[8:11]
	v_mfma_f32_16x16x32_bf16 v[52:55], v[150:153], v[232:235], v[52:55]
	v_mfma_f32_16x16x32_bf16 v[36:39], v[150:153], v[236:239], v[36:39]
	v_mfma_f32_16x16x32_bf16 v[20:23], v[150:153], v[240:243], v[20:23]
	v_mfma_f32_16x16x32_bf16 v[4:7], v[150:153], v[244:247], v[4:7]
	v_mfma_f32_16x16x32_bf16 v[48:51], v[158:161], v[232:235], v[48:51]
	v_mfma_f32_16x16x32_bf16 v[32:35], v[158:161], v[236:239], v[32:35]
	v_mfma_f32_16x16x32_bf16 v[16:19], v[158:161], v[240:243], v[16:19]
	v_mfma_f32_16x16x32_bf16 v[0:3], v[158:161], v[244:247], v[0:3]
	s_waitcnt vmcnt(8)
	s_barrier
	v_add_u32_e32 v112, 0x8000, v139
	v_or_b32_e32 v141, 0x8000, v140
	ds_read_b128 v[130:133], v141
	ds_read_b128 v[134:137], v141 offset:1024
	ds_read_b128 v[142:145], v141 offset:2048
	ds_read_b128 v[146:149], v141 offset:3072
	ds_read_b128 v[150:153], v112
	ds_read_b128 v[158:161], v112 offset:1024
	ds_read_b128 v[162:165], v112 offset:2048
	ds_read_b128 v[166:169], v112 offset:3072
	v_add_u32_e32 v141, 0x10000, v139
	s_waitcnt lgkmcnt(0)
	v_or_b32_e32 v154, 0x10000, v140
	v_mfma_f32_16x16x32_bf16 v[126:129], v[130:133], v[150:153], v[126:129]
	v_add_u32_e32 v139, 0x18000, v139
	s_lshl_b32 s8, s6, 8
	v_and_b32_e32 v170, 15, v138
	v_mfma_f32_16x16x32_bf16 v[122:125], v[134:137], v[150:153], v[122:125]
	s_and_b32 s18, s8, 0xffffc000
	s_ashr_i32 s7, s6, 1
	s_and_b32 s7, s7, 0xffffff80
	v_mfma_f32_16x16x32_bf16 v[118:121], v[142:145], v[150:153], v[118:121]
	s_and_b32 s6, s6, 0xc0
	s_add_i32 s8, s4, s7
	s_or_b32 s4, s5, s6
	v_mfma_f32_16x16x32_bf16 v[114:117], v[146:149], v[150:153], v[114:117]
	s_ashr_i32 s10, s4, 6
	s_ashr_i32 s11, s10, 31
	v_mfma_f32_16x16x32_bf16 v[108:111], v[130:133], v[158:161], v[108:111]
	v_mfma_f32_16x16x32_bf16 v[104:107], v[134:137], v[158:161], v[104:107]
	v_mfma_f32_16x16x32_bf16 v[100:103], v[142:145], v[158:161], v[100:103]
	v_mfma_f32_16x16x32_bf16 v[96:99], v[146:149], v[158:161], v[96:99]
	v_mfma_f32_16x16x32_bf16 v[92:95], v[130:133], v[162:165], v[92:95]
	v_mfma_f32_16x16x32_bf16 v[88:91], v[134:137], v[162:165], v[88:91]
	v_mfma_f32_16x16x32_bf16 v[84:87], v[142:145], v[162:165], v[84:87]
	v_mfma_f32_16x16x32_bf16 v[80:83], v[146:149], v[162:165], v[80:83]
	v_mfma_f32_16x16x32_bf16 v[76:79], v[130:133], v[166:169], v[76:79]
	v_mfma_f32_16x16x32_bf16 v[72:75], v[134:137], v[166:169], v[72:75]
	v_mfma_f32_16x16x32_bf16 v[68:71], v[142:145], v[166:169], v[68:71]
	v_mfma_f32_16x16x32_bf16 v[64:67], v[146:149], v[166:169], v[64:67]
	ds_read_b128 v[150:153], v112 offset:4096
	ds_read_b128 v[158:161], v112 offset:5120
	ds_read_b128 v[162:165], v112 offset:6144
	ds_read_b128 v[166:169], v112 offset:7168
	s_waitcnt lgkmcnt(0)
	s_waitcnt vmcnt(4)
	s_barrier
	v_mfma_f32_16x16x32_bf16 v[60:63], v[130:133], v[150:153], v[60:63]
	v_and_b32_e32 v112, 63, v138
	v_mfma_f32_16x16x32_bf16 v[56:59], v[134:137], v[150:153], v[56:59]
	v_mfma_f32_16x16x32_bf16 v[52:55], v[142:145], v[150:153], v[52:55]
	v_mfma_f32_16x16x32_bf16 v[48:51], v[146:149], v[150:153], v[48:51]
	v_mfma_f32_16x16x32_bf16 v[44:47], v[130:133], v[158:161], v[44:47]
	v_mfma_f32_16x16x32_bf16 v[40:43], v[134:137], v[158:161], v[40:43]
	v_mfma_f32_16x16x32_bf16 v[36:39], v[142:145], v[158:161], v[36:39]
	v_mfma_f32_16x16x32_bf16 v[32:35], v[146:149], v[158:161], v[32:35]
	v_mfma_f32_16x16x32_bf16 v[28:31], v[130:133], v[162:165], v[28:31]
	v_mfma_f32_16x16x32_bf16 v[24:27], v[134:137], v[162:165], v[24:27]
	v_mfma_f32_16x16x32_bf16 v[20:23], v[142:145], v[162:165], v[20:23]
	v_mfma_f32_16x16x32_bf16 v[16:19], v[146:149], v[162:165], v[16:19]
	v_mfma_f32_16x16x32_bf16 v[12:15], v[130:133], v[166:169], v[12:15]
	v_mfma_f32_16x16x32_bf16 v[8:11], v[134:137], v[166:169], v[8:11]
	v_mfma_f32_16x16x32_bf16 v[4:7], v[142:145], v[166:169], v[4:7]
	v_mfma_f32_16x16x32_bf16 v[0:3], v[146:149], v[166:169], v[0:3]
	ds_read_b128 v[130:133], v154
	ds_read_b128 v[134:137], v154 offset:1024
	ds_read_b128 v[142:145], v154 offset:2048
	ds_read_b128 v[146:149], v154 offset:3072
	ds_read_b128 v[150:153], v141
	ds_read_b128 v[158:161], v141 offset:1024
	ds_read_b128 v[162:165], v141 offset:2048
	ds_read_b128 v[166:169], v141 offset:3072
	s_nop 0
	s_waitcnt lgkmcnt(0)
	s_nop 0
	v_mfma_f32_16x16x32_bf16 v[126:129], v[130:133], v[150:153], v[126:129]
	v_mfma_f32_16x16x32_bf16 v[122:125], v[134:137], v[150:153], v[122:125]
	v_mfma_f32_16x16x32_bf16 v[118:121], v[142:145], v[150:153], v[118:121]
	v_mfma_f32_16x16x32_bf16 v[114:117], v[146:149], v[150:153], v[114:117]
	v_mfma_f32_16x16x32_bf16 v[108:111], v[130:133], v[158:161], v[108:111]
	v_mfma_f32_16x16x32_bf16 v[104:107], v[134:137], v[158:161], v[104:107]
	v_mfma_f32_16x16x32_bf16 v[100:103], v[142:145], v[158:161], v[100:103]
	v_mfma_f32_16x16x32_bf16 v[150:153], v[146:149], v[158:161], v[96:99]
	v_mfma_f32_16x16x32_bf16 v[92:95], v[130:133], v[162:165], v[92:95]
	v_mfma_f32_16x16x32_bf16 v[88:91], v[134:137], v[162:165], v[88:91]
	v_mfma_f32_16x16x32_bf16 v[84:87], v[142:145], v[162:165], v[84:87]
	v_mfma_f32_16x16x32_bf16 v[80:83], v[146:149], v[162:165], v[80:83]
	v_mfma_f32_16x16x32_bf16 v[76:79], v[130:133], v[166:169], v[76:79]
	v_mfma_f32_16x16x32_bf16 v[72:75], v[134:137], v[166:169], v[72:75]
	v_mfma_f32_16x16x32_bf16 v[68:71], v[142:145], v[166:169], v[68:71]
	v_mfma_f32_16x16x32_bf16 v[64:67], v[146:149], v[166:169], v[64:67]
	ds_read_b128 v[96:99], v141 offset:4096
	ds_read_b128 v[158:161], v141 offset:5120
	ds_read_b128 v[162:165], v141 offset:6144
	ds_read_b128 v[166:169], v141 offset:7168
	s_waitcnt lgkmcnt(0)
	s_waitcnt vmcnt(0)
	s_barrier
	v_mfma_f32_16x16x32_bf16 v[60:63], v[130:133], v[96:99], v[60:63]
	v_mfma_f32_16x16x32_bf16 v[56:59], v[134:137], v[96:99], v[56:59]
	v_mfma_f32_16x16x32_bf16 v[52:55], v[142:145], v[96:99], v[52:55]
	v_mfma_f32_16x16x32_bf16 v[48:51], v[146:149], v[96:99], v[48:51]
	v_mfma_f32_16x16x32_bf16 v[44:47], v[130:133], v[158:161], v[44:47]
	v_mfma_f32_16x16x32_bf16 v[40:43], v[134:137], v[158:161], v[40:43]
	v_mfma_f32_16x16x32_bf16 v[36:39], v[142:145], v[158:161], v[36:39]
	v_mfma_f32_16x16x32_bf16 v[32:35], v[146:149], v[158:161], v[32:35]
	v_mfma_f32_16x16x32_bf16 v[28:31], v[130:133], v[162:165], v[28:31]
	v_mfma_f32_16x16x32_bf16 v[24:27], v[134:137], v[162:165], v[24:27]
	v_mfma_f32_16x16x32_bf16 v[20:23], v[142:145], v[162:165], v[20:23]
	v_mfma_f32_16x16x32_bf16 v[16:19], v[146:149], v[162:165], v[16:19]
	v_mfma_f32_16x16x32_bf16 v[12:15], v[130:133], v[166:169], v[12:15]
	v_mfma_f32_16x16x32_bf16 v[8:11], v[134:137], v[166:169], v[8:11]
	v_mfma_f32_16x16x32_bf16 v[4:7], v[142:145], v[166:169], v[4:7]
	v_mfma_f32_16x16x32_bf16 v[0:3], v[146:149], v[166:169], v[0:3]
	v_or_b32_e32 v148, 0x18000, v140
	ds_read_b128 v[130:133], v148
	ds_read_b128 v[134:137], v148 offset:1024
	ds_read_b128 v[140:143], v148 offset:2048
	ds_read_b128 v[144:147], v148 offset:3072
	ds_read_b128 v[96:99], v139
	ds_read_b128 v[158:161], v139 offset:1024
	ds_read_b128 v[162:165], v139 offset:2048
	ds_read_b128 v[166:169], v139 offset:3072
	s_nop 0
	s_waitcnt lgkmcnt(0)
	s_nop 0
	v_mfma_f32_16x16x32_bf16 v[126:129], v[130:133], v[96:99], v[126:129]
	v_mfma_f32_16x16x32_bf16 v[174:177], v[134:137], v[96:99], v[122:125]
	v_mfma_f32_16x16x32_bf16 v[182:185], v[140:143], v[96:99], v[118:121]
	v_mfma_f32_16x16x32_bf16 v[114:117], v[144:147], v[96:99], v[114:117]
	v_mfma_f32_16x16x32_bf16 v[96:99], v[140:143], v[158:161], v[100:103]
	v_mfma_f32_16x16x32_bf16 v[100:103], v[144:147], v[158:161], v[150:153]
	ds_read_b128 v[118:121], v139 offset:4096
	ds_read_b128 v[122:125], v139 offset:5120
	ds_read_b128 v[148:151], v139 offset:6144
	ds_read_b128 v[152:155], v139 offset:7168
	s_waitcnt lgkmcnt(0)
	s_barrier
	v_mfma_f32_16x16x32_bf16 v[60:63], v[130:133], v[118:121], v[60:63]
	v_mfma_f32_16x16x32_bf16 v[56:59], v[134:137], v[118:121], v[56:59]
	v_mfma_f32_16x16x32_bf16 v[52:55], v[140:143], v[118:121], v[52:55]
	v_mfma_f32_16x16x32_bf16 v[48:51], v[144:147], v[118:121], v[48:51]
	v_bfe_u32 v119, v138, 5, 1
	v_lshrrev_b32_e32 v121, 1, v138
	v_lshlrev_b32_e32 v118, 7, v170
	v_mfma_f32_16x16x32_bf16 v[44:47], v[130:133], v[122:125], v[44:47]
	v_and_b32_e32 v121, 8, v121
	v_and_b32_e32 v120, 7, v138
	v_mfma_f32_16x16x32_bf16 v[40:43], v[134:137], v[122:125], v[40:43]
	v_mfma_f32_16x16x32_bf16 v[36:39], v[140:143], v[122:125], v[36:39]
	v_mfma_f32_16x16x32_bf16 v[32:35], v[144:147], v[122:125], v[32:35]
	v_mul_f32_e32 v125, v127, v127
	v_bitop3_b32 v124, v119, v138, 7 bitop3:0x78
	v_or3_b32 v123, s18, v118, v121
	v_fmac_f32_e32 v125, v126, v126
	v_lshlrev_b32_e32 v124, 4, v124
	v_fmac_f32_e32 v125, v128, v128
	v_cvt_pk_bf16_f32 v126, v126, v127
	v_cvt_pk_bf16_f32 v127, v128, v129
	v_or_b32_e32 v128, v123, v124
	s_waitcnt vmcnt(0)
	ds_write_b64 v128, v[126:127]
	v_mul_f32_e32 v126, v175, v175
	v_fmac_f32_e32 v126, v174, v174
	v_fmac_f32_e32 v126, v176, v176
	v_fmac_f32_e32 v125, v129, v129
	v_fmac_f32_e32 v126, v177, v177
	v_add_f32_e32 v125, v125, v126
	v_bitop3_b32 v126, v119, v120, 2 bitop3:0x36
	v_lshlrev_b32_e32 v126, 4, v126
	v_cvt_pk_bf16_f32 v128, v174, v175
	v_cvt_pk_bf16_f32 v129, v176, v177
	v_or_b32_e32 v127, v123, v126
	ds_write_b64 v127, v[128:129]
	v_mul_f32_e32 v127, v183, v183
	v_fmac_f32_e32 v127, v182, v182
	v_fmac_f32_e32 v127, v184, v184
	v_fmac_f32_e32 v127, v185, v185
	v_add_f32_e32 v127, v125, v127
	v_bitop3_b32 v125, v119, v120, 4 bitop3:0x36
	v_lshlrev_b32_e32 v125, 4, v125
	v_mfma_f32_16x16x32_bf16 v[108:111], v[130:133], v[158:161], v[108:111]
	v_cvt_pk_bf16_f32 v128, v182, v183
	v_cvt_pk_bf16_f32 v129, v184, v185
	v_and_b32_e32 v121, 64, v172
	v_mfma_f32_16x16x32_bf16 v[92:95], v[130:133], v[162:165], v[92:95]
	v_xor_b32_e32 v118, 16, v172
	v_add_u32_e32 v122, 64, v121
	v_cmp_lt_i32_e32 vcc, v118, v122
	v_mfma_f32_16x16x32_bf16 v[76:79], v[130:133], v[166:169], v[76:79]
	s_nop 0
	v_cndmask_b32_e32 v118, v172, v118, vcc
	v_lshlrev_b32_e32 v121, 2, v118
	v_mfma_f32_16x16x32_bf16 v[28:31], v[130:133], v[148:151], v[28:31]
	v_xor_b32_e32 v118, 32, v172
	v_cmp_lt_i32_e32 vcc, v118, v122
	v_mfma_f32_16x16x32_bf16 v[12:15], v[130:133], v[152:155], v[12:15]
	v_or_b32_e32 v130, v123, v125
	ds_write_b64 v130, v[128:129]
	v_mul_f32_e32 v128, v115, v115
	v_fmac_f32_e32 v128, v114, v114
	v_fmac_f32_e32 v128, v116, v116
	v_fmac_f32_e32 v128, v117, v117
	v_add_f32_e32 v127, v127, v128
	v_cvt_pk_bf16_f32 v128, v114, v115
	v_bitop3_b32 v114, v119, v120, 6 bitop3:0x36
	v_lshlrev_b32_e32 v114, 4, v114
	v_cvt_pk_bf16_f32 v129, v116, v117
	v_or_b32_e32 v115, v123, v114
	ds_write_b64 v115, v[128:129]
	ds_bpermute_b32 v115, v121, v127
	v_cndmask_b32_e32 v118, v172, v118, vcc
	v_lshlrev_b32_e32 v122, 2, v118
	v_mfma_f32_16x16x32_bf16 v[104:107], v[134:137], v[158:161], v[104:107]
	v_cmp_gt_u32_e32 vcc, 16, v112
	s_waitcnt lgkmcnt(0)
	v_add_f32_e32 v115, v127, v115
	ds_bpermute_b32 v116, v122, v115
	v_mfma_f32_16x16x32_bf16 v[88:91], v[134:137], v[162:165], v[88:91]
	v_or_b32_e32 v118, s8, v170
	v_mfma_f32_16x16x32_bf16 v[84:87], v[140:143], v[162:165], v[84:87]
	v_mfma_f32_16x16x32_bf16 v[80:83], v[144:147], v[162:165], v[80:83]
	v_mfma_f32_16x16x32_bf16 v[72:75], v[134:137], v[166:169], v[72:75]
	v_mfma_f32_16x16x32_bf16 v[68:71], v[140:143], v[166:169], v[68:71]
	v_mfma_f32_16x16x32_bf16 v[64:67], v[144:147], v[166:169], v[64:67]
	v_mfma_f32_16x16x32_bf16 v[24:27], v[134:137], v[148:151], v[24:27]
	v_mfma_f32_16x16x32_bf16 v[20:23], v[140:143], v[148:151], v[20:23]
	v_mfma_f32_16x16x32_bf16 v[16:19], v[144:147], v[148:151], v[16:19]
	v_mfma_f32_16x16x32_bf16 v[8:11], v[134:137], v[152:155], v[8:11]
	v_mfma_f32_16x16x32_bf16 v[4:7], v[140:143], v[152:155], v[4:7]
	v_mfma_f32_16x16x32_bf16 v[0:3], v[144:147], v[152:155], v[0:3]
	s_and_saveexec_b64 s[6:7], vcc
	s_cbranch_execz .LBB0_545
	v_ashrrev_i32_e32 v119, 31, v118
	s_waitcnt lgkmcnt(0)
	v_add_f32_e32 v115, v115, v116
	v_lshlrev_b64 v[116:117], 6, v[118:119]
	v_lshl_add_u64 v[116:117], s[44:45], 0, v[116:117]
	v_lshl_add_u64 v[116:117], s[10:11], 2, v[116:117]
	global_store_dword v[116:117], v115, off

.Lgsk2_loop:
	s_add_i32 s8, s5, 0xfffe8000
	s_and_b32 s9, s5, 0x18000
	s_waitcnt vmcnt(8) lgkmcnt(0)
	s_barrier
	s_and_b32 s8, s8, 0x18000
	s_add_i32 s9, s4, s9
	v_add_u32_e32 v128, s8, v160
	v_or_b32_e32 v170, s8, v161
	s_add_i32 s11, s9, 0x400
	s_add_i32 s10, s9, 0x800
	s_add_i32 s8, s9, 0xc00
	s_add_i32 s5, s5, 0x8000
	s_cmp_eq_u32 s5, 0x100000
	ds_read_b128 v[182:185], v128
	ds_read_b128 v[186:189], v128 offset:1024
	ds_read_b128 v[190:193], v128 offset:2048
	ds_read_b128 v[194:197], v128 offset:3072
	v_mfma_f32_16x16x32_bf16 v[60:63], v[162:165], v[232:235], v[60:63]
	s_mov_b32 m0, s9
	v_mfma_f32_16x16x32_bf16 v[44:47], v[162:165], v[236:239], v[44:47]
	global_load_lds_dwordx4 v[136:137], off
	v_lshl_add_u64 v[136:137], v[136:137], 0, 64
	v_mfma_f32_16x16x32_bf16 v[28:31], v[162:165], v[240:243], v[28:31]
	s_mov_b32 m0, s11
	v_mfma_f32_16x16x32_bf16 v[12:15], v[162:165], v[244:247], v[12:15]
	global_load_lds_dwordx4 v[134:135], off
	v_lshl_add_u64 v[134:135], v[134:135], 0, 64
	v_mfma_f32_16x16x32_bf16 v[56:59], v[166:169], v[232:235], v[56:59]
	ds_read_b128 v[162:165], v170
	s_mov_b32 m0, s10
	v_mfma_f32_16x16x32_bf16 v[40:43], v[166:169], v[236:239], v[40:43]
	global_load_lds_dwordx4 v[132:133], off
	v_lshl_add_u64 v[132:133], v[132:133], 0, 64
	v_mfma_f32_16x16x32_bf16 v[24:27], v[166:169], v[240:243], v[24:27]
	s_mov_b32 m0, s8
	v_mfma_f32_16x16x32_bf16 v[8:11], v[166:169], v[244:247], v[8:11]
	global_load_lds_dwordx4 v[130:131], off
	v_lshl_add_u64 v[130:131], v[130:131], 0, 64
	v_mfma_f32_16x16x32_bf16 v[52:55], v[174:177], v[232:235], v[52:55]
	ds_read_b128 v[166:169], v170 offset:1024
	v_mfma_f32_16x16x32_bf16 v[36:39], v[174:177], v[236:239], v[36:39]
	v_mfma_f32_16x16x32_bf16 v[20:23], v[174:177], v[240:243], v[20:23]
	v_mfma_f32_16x16x32_bf16 v[4:7], v[174:177], v[244:247], v[4:7]
	v_mfma_f32_16x16x32_bf16 v[48:51], v[178:181], v[232:235], v[48:51]
	ds_read_b128 v[174:177], v170 offset:2048
	v_mfma_f32_16x16x32_bf16 v[32:35], v[178:181], v[236:239], v[32:35]
	v_mfma_f32_16x16x32_bf16 v[16:19], v[178:181], v[240:243], v[16:19]
	v_mfma_f32_16x16x32_bf16 v[0:3], v[178:181], v[244:247], v[0:3]
	s_waitcnt lgkmcnt(2)
	v_mfma_f32_16x16x32_bf16 v[124:127], v[162:165], v[182:185], v[124:127]
	ds_read_b128 v[178:181], v170 offset:3072
	v_mfma_f32_16x16x32_bf16 v[108:111], v[162:165], v[186:189], v[108:111]
	ds_read_b128 v[232:235], v128 offset:4096
	ds_read_b128 v[236:239], v128 offset:5120
	v_mfma_f32_16x16x32_bf16 v[92:95], v[162:165], v[190:193], v[92:95]
	ds_read_b128 v[240:243], v128 offset:6144
	ds_read_b128 v[244:247], v128 offset:7168
	v_mfma_f32_16x16x32_bf16 v[76:79], v[162:165], v[194:197], v[76:79]
	s_waitcnt lgkmcnt(6)
	v_mfma_f32_16x16x32_bf16 v[120:123], v[166:169], v[182:185], v[120:123]
	v_mfma_f32_16x16x32_bf16 v[104:107], v[166:169], v[186:189], v[104:107]
	v_mfma_f32_16x16x32_bf16 v[88:91], v[166:169], v[190:193], v[88:91]
	v_mfma_f32_16x16x32_bf16 v[72:75], v[166:169], v[194:197], v[72:75]
	s_waitcnt lgkmcnt(5)
	v_mfma_f32_16x16x32_bf16 v[116:119], v[174:177], v[182:185], v[116:119]
	v_mfma_f32_16x16x32_bf16 v[100:103], v[174:177], v[186:189], v[100:103]
	v_mfma_f32_16x16x32_bf16 v[84:87], v[174:177], v[190:193], v[84:87]
	v_mfma_f32_16x16x32_bf16 v[68:71], v[174:177], v[194:197], v[68:71]
	s_waitcnt lgkmcnt(4)
	v_mfma_f32_16x16x32_bf16 v[112:115], v[178:181], v[182:185], v[112:115]
	v_mfma_f32_16x16x32_bf16 v[96:99], v[178:181], v[186:189], v[96:99]
	v_mfma_f32_16x16x32_bf16 v[80:83], v[178:181], v[190:193], v[80:83]
	v_mfma_f32_16x16x32_bf16 v[64:67], v[178:181], v[194:197], v[64:67]
	s_cbranch_scc0 .Lgsk2_loop
	s_waitcnt lgkmcnt(0)
	v_mfma_f32_16x16x32_bf16 v[60:63], v[162:165], v[232:235], v[60:63]
	v_mfma_f32_16x16x32_bf16 v[44:47], v[162:165], v[236:239], v[44:47]
	v_mfma_f32_16x16x32_bf16 v[28:31], v[162:165], v[240:243], v[28:31]
	v_mfma_f32_16x16x32_bf16 v[12:15], v[162:165], v[244:247], v[12:15]
	v_mfma_f32_16x16x32_bf16 v[56:59], v[166:169], v[232:235], v[56:59]
	v_mfma_f32_16x16x32_bf16 v[40:43], v[166:169], v[236:239], v[40:43]
	v_mfma_f32_16x16x32_bf16 v[24:27], v[166:169], v[240:243], v[24:27]
	v_mfma_f32_16x16x32_bf16 v[8:11], v[166:169], v[244:247], v[8:11]
	v_mfma_f32_16x16x32_bf16 v[52:55], v[174:177], v[232:235], v[52:55]
	v_mfma_f32_16x16x32_bf16 v[36:39], v[174:177], v[236:239], v[36:39]
	v_mfma_f32_16x16x32_bf16 v[20:23], v[174:177], v[240:243], v[20:23]
	v_mfma_f32_16x16x32_bf16 v[4:7], v[174:177], v[244:247], v[4:7]
	v_mfma_f32_16x16x32_bf16 v[48:51], v[178:181], v[232:235], v[48:51]
	v_mfma_f32_16x16x32_bf16 v[32:35], v[178:181], v[236:239], v[32:35]
	v_mfma_f32_16x16x32_bf16 v[16:19], v[178:181], v[240:243], v[16:19]
	v_mfma_f32_16x16x32_bf16 v[0:3], v[178:181], v[244:247], v[0:3]
	s_waitcnt vmcnt(8)
	s_barrier
	v_add_u32_e32 v128, 0x8000, v160
	v_or_b32_e32 v170, 0x8000, v161
	ds_read_b128 v[130:133], v170
	ds_read_b128 v[134:137], v170 offset:1024
	ds_read_b128 v[162:165], v170 offset:2048
	ds_read_b128 v[166:169], v170 offset:3072
	ds_read_b128 v[174:177], v128
	ds_read_b128 v[178:181], v128 offset:1024
	ds_read_b128 v[182:185], v128 offset:2048
	ds_read_b128 v[186:189], v128 offset:3072
	v_or_b32_e32 v170, 0x10000, v161
	s_waitcnt lgkmcnt(0)
	v_or_b32_e32 v173, 0x18000, v161
	v_mfma_f32_16x16x32_bf16 v[124:127], v[130:133], v[174:177], v[124:127]
	s_cmp_eq_u32 s13, 2
	s_cselect_b64 s[8:9], -1, 0
	s_cmp_eq_u32 s13, 3
	v_mfma_f32_16x16x32_bf16 v[120:123], v[134:137], v[174:177], v[120:123]
	s_cselect_b64 s[4:5], -1, 0
	s_and_b64 vcc, exec, s[4:5]
	v_mfma_f32_16x16x32_bf16 v[116:119], v[162:165], v[174:177], v[116:119]
	v_mfma_f32_16x16x32_bf16 v[112:115], v[166:169], v[174:177], v[112:115]
	v_mfma_f32_16x16x32_bf16 v[108:111], v[130:133], v[178:181], v[108:111]
	v_mfma_f32_16x16x32_bf16 v[104:107], v[134:137], v[178:181], v[104:107]
	v_mfma_f32_16x16x32_bf16 v[100:103], v[162:165], v[178:181], v[100:103]
	v_mfma_f32_16x16x32_bf16 v[96:99], v[166:169], v[178:181], v[96:99]
	v_mfma_f32_16x16x32_bf16 v[92:95], v[130:133], v[182:185], v[92:95]
	v_mfma_f32_16x16x32_bf16 v[88:91], v[134:137], v[182:185], v[88:91]
	v_mfma_f32_16x16x32_bf16 v[84:87], v[162:165], v[182:185], v[84:87]
	v_mfma_f32_16x16x32_bf16 v[80:83], v[166:169], v[182:185], v[80:83]
	v_mfma_f32_16x16x32_bf16 v[76:79], v[130:133], v[186:189], v[76:79]
	v_mfma_f32_16x16x32_bf16 v[72:75], v[134:137], v[186:189], v[72:75]
	v_mfma_f32_16x16x32_bf16 v[68:71], v[162:165], v[186:189], v[68:71]
	v_mfma_f32_16x16x32_bf16 v[64:67], v[166:169], v[186:189], v[64:67]
	ds_read_b128 v[174:177], v128 offset:4096
	ds_read_b128 v[178:181], v128 offset:5120
	ds_read_b128 v[182:185], v128 offset:6144
	ds_read_b128 v[186:189], v128 offset:7168
	s_waitcnt lgkmcnt(0)
	s_waitcnt vmcnt(4)
	s_barrier
	v_mfma_f32_16x16x32_bf16 v[60:63], v[130:133], v[174:177], v[60:63]
	v_add_u32_e32 v128, 0x10000, v160
	v_mfma_f32_16x16x32_bf16 v[56:59], v[134:137], v[174:177], v[56:59]
	v_mfma_f32_16x16x32_bf16 v[52:55], v[162:165], v[174:177], v[52:55]
	v_mfma_f32_16x16x32_bf16 v[48:51], v[166:169], v[174:177], v[48:51]
	v_mfma_f32_16x16x32_bf16 v[44:47], v[130:133], v[178:181], v[44:47]
	v_mfma_f32_16x16x32_bf16 v[40:43], v[134:137], v[178:181], v[40:43]
	v_mfma_f32_16x16x32_bf16 v[36:39], v[162:165], v[178:181], v[36:39]
	v_mfma_f32_16x16x32_bf16 v[32:35], v[166:169], v[178:181], v[32:35]
	v_mfma_f32_16x16x32_bf16 v[28:31], v[130:133], v[182:185], v[28:31]
	v_mfma_f32_16x16x32_bf16 v[24:27], v[134:137], v[182:185], v[24:27]
	v_mfma_f32_16x16x32_bf16 v[20:23], v[162:165], v[182:185], v[20:23]
	v_mfma_f32_16x16x32_bf16 v[16:19], v[166:169], v[182:185], v[16:19]
	v_mfma_f32_16x16x32_bf16 v[12:15], v[130:133], v[186:189], v[12:15]
	v_mfma_f32_16x16x32_bf16 v[8:11], v[134:137], v[186:189], v[8:11]
	v_mfma_f32_16x16x32_bf16 v[4:7], v[162:165], v[186:189], v[4:7]
	v_mfma_f32_16x16x32_bf16 v[0:3], v[166:169], v[186:189], v[0:3]
	ds_read_b128 v[130:133], v170
	ds_read_b128 v[134:137], v170 offset:1024
	ds_read_b128 v[162:165], v170 offset:2048
	ds_read_b128 v[166:169], v170 offset:3072
	ds_read_b128 v[174:177], v128
	ds_read_b128 v[178:181], v128 offset:1024
	ds_read_b128 v[182:185], v128 offset:2048
	ds_read_b128 v[186:189], v128 offset:3072
	s_nop 0
	s_waitcnt lgkmcnt(0)
	s_nop 0
	v_mfma_f32_16x16x32_bf16 v[124:127], v[130:133], v[174:177], v[124:127]
	v_mfma_f32_16x16x32_bf16 v[120:123], v[134:137], v[174:177], v[120:123]
	v_mfma_f32_16x16x32_bf16 v[116:119], v[162:165], v[174:177], v[116:119]
	v_mfma_f32_16x16x32_bf16 v[112:115], v[166:169], v[174:177], v[112:115]
	v_mfma_f32_16x16x32_bf16 v[108:111], v[130:133], v[178:181], v[108:111]
	v_mfma_f32_16x16x32_bf16 v[104:107], v[134:137], v[178:181], v[104:107]
	v_mfma_f32_16x16x32_bf16 v[100:103], v[162:165], v[178:181], v[100:103]
	v_mfma_f32_16x16x32_bf16 v[96:99], v[166:169], v[178:181], v[96:99]
	v_mfma_f32_16x16x32_bf16 v[92:95], v[130:133], v[182:185], v[92:95]
	v_mfma_f32_16x16x32_bf16 v[88:91], v[134:137], v[182:185], v[88:91]
	v_mfma_f32_16x16x32_bf16 v[84:87], v[162:165], v[182:185], v[84:87]
	v_mfma_f32_16x16x32_bf16 v[80:83], v[166:169], v[182:185], v[80:83]
	v_mfma_f32_16x16x32_bf16 v[76:79], v[130:133], v[186:189], v[76:79]
	v_mfma_f32_16x16x32_bf16 v[72:75], v[134:137], v[186:189], v[72:75]
	v_mfma_f32_16x16x32_bf16 v[68:71], v[162:165], v[186:189], v[68:71]
	v_mfma_f32_16x16x32_bf16 v[64:67], v[166:169], v[186:189], v[64:67]
	ds_read_b128 v[174:177], v128 offset:4096
	ds_read_b128 v[178:181], v128 offset:5120
	ds_read_b128 v[182:185], v128 offset:6144
	ds_read_b128 v[186:189], v128 offset:7168
	s_waitcnt lgkmcnt(0)
	s_waitcnt vmcnt(0)
	s_barrier
	v_mfma_f32_16x16x32_bf16 v[60:63], v[130:133], v[174:177], v[60:63]
	v_add_u32_e32 v128, 0x18000, v160
	v_mfma_f32_16x16x32_bf16 v[56:59], v[134:137], v[174:177], v[56:59]
	v_mfma_f32_16x16x32_bf16 v[52:55], v[162:165], v[174:177], v[52:55]
	v_mfma_f32_16x16x32_bf16 v[48:51], v[166:169], v[174:177], v[48:51]
	v_mfma_f32_16x16x32_bf16 v[44:47], v[130:133], v[178:181], v[44:47]
	v_mfma_f32_16x16x32_bf16 v[40:43], v[134:137], v[178:181], v[40:43]
	v_mfma_f32_16x16x32_bf16 v[36:39], v[162:165], v[178:181], v[36:39]
	v_mfma_f32_16x16x32_bf16 v[32:35], v[166:169], v[178:181], v[32:35]
	v_mfma_f32_16x16x32_bf16 v[28:31], v[130:133], v[182:185], v[28:31]
	v_mfma_f32_16x16x32_bf16 v[24:27], v[134:137], v[182:185], v[24:27]
	v_mfma_f32_16x16x32_bf16 v[20:23], v[162:165], v[182:185], v[20:23]
	v_mfma_f32_16x16x32_bf16 v[16:19], v[166:169], v[182:185], v[16:19]
	v_mfma_f32_16x16x32_bf16 v[12:15], v[130:133], v[186:189], v[12:15]
	v_mfma_f32_16x16x32_bf16 v[8:11], v[134:137], v[186:189], v[8:11]
	v_mfma_f32_16x16x32_bf16 v[4:7], v[162:165], v[186:189], v[4:7]
	v_mfma_f32_16x16x32_bf16 v[0:3], v[166:169], v[186:189], v[0:3]
	ds_read_b128 v[130:133], v173
	ds_read_b128 v[134:137], v173 offset:1024
	ds_read_b128 v[160:163], v173 offset:2048
	ds_read_b128 v[164:167], v173 offset:3072
	ds_read_b128 v[168:171], v128
	ds_read_b128 v[174:177], v128 offset:1024
	ds_read_b128 v[178:181], v128 offset:2048
	ds_read_b128 v[182:185], v128 offset:3072
	s_nop 0
	s_waitcnt lgkmcnt(0)
	s_nop 0
	v_mfma_f32_16x16x32_bf16 v[186:189], v[130:133], v[168:171], v[124:127]
	v_mfma_f32_16x16x32_bf16 v[120:123], v[134:137], v[168:171], v[120:123]
	v_mfma_f32_16x16x32_bf16 v[116:119], v[160:163], v[168:171], v[116:119]
	v_mfma_f32_16x16x32_bf16 v[112:115], v[164:167], v[168:171], v[112:115]
	v_mfma_f32_16x16x32_bf16 v[108:111], v[130:133], v[174:177], v[108:111]
	v_mfma_f32_16x16x32_bf16 v[104:107], v[134:137], v[174:177], v[104:107]
	v_mfma_f32_16x16x32_bf16 v[100:103], v[160:163], v[174:177], v[100:103]
	v_mfma_f32_16x16x32_bf16 v[96:99], v[164:167], v[174:177], v[96:99]
	v_mfma_f32_16x16x32_bf16 v[92:95], v[130:133], v[178:181], v[92:95]
	v_mfma_f32_16x16x32_bf16 v[88:91], v[134:137], v[178:181], v[88:91]
	v_mfma_f32_16x16x32_bf16 v[84:87], v[160:163], v[178:181], v[84:87]
	v_mfma_f32_16x16x32_bf16 v[80:83], v[164:167], v[178:181], v[80:83]
	ds_read_b128 v[124:127], v128 offset:4096
	ds_read_b128 v[168:171], v128 offset:5120
	ds_read_b128 v[174:177], v128 offset:6144
	ds_read_b128 v[178:181], v128 offset:7168
	s_waitcnt lgkmcnt(0)
	s_barrier
	v_mfma_f32_16x16x32_bf16 v[76:79], v[130:133], v[182:185], v[76:79]
	v_mfma_f32_16x16x32_bf16 v[72:75], v[134:137], v[182:185], v[72:75]
	v_mfma_f32_16x16x32_bf16 v[68:71], v[160:163], v[182:185], v[68:71]
	v_mfma_f32_16x16x32_bf16 v[64:67], v[164:167], v[182:185], v[64:67]
	v_mfma_f32_16x16x32_bf16 v[60:63], v[130:133], v[124:127], v[60:63]
	v_mfma_f32_16x16x32_bf16 v[56:59], v[134:137], v[124:127], v[56:59]
	v_mfma_f32_16x16x32_bf16 v[52:55], v[160:163], v[124:127], v[52:55]
	v_mfma_f32_16x16x32_bf16 v[48:51], v[164:167], v[124:127], v[48:51]
	v_mfma_f32_16x16x32_bf16 v[44:47], v[130:133], v[168:171], v[44:47]
	v_mfma_f32_16x16x32_bf16 v[40:43], v[134:137], v[168:171], v[40:43]
	v_mfma_f32_16x16x32_bf16 v[36:39], v[160:163], v[168:171], v[36:39]
	v_mfma_f32_16x16x32_bf16 v[32:35], v[164:167], v[168:171], v[32:35]
	v_mfma_f32_16x16x32_bf16 v[28:31], v[130:133], v[174:177], v[28:31]
	v_mfma_f32_16x16x32_bf16 v[24:27], v[134:137], v[174:177], v[24:27]
	v_mfma_f32_16x16x32_bf16 v[20:23], v[160:163], v[174:177], v[20:23]
	v_mfma_f32_16x16x32_bf16 v[16:19], v[164:167], v[174:177], v[16:19]
	v_mfma_f32_16x16x32_bf16 v[12:15], v[130:133], v[178:181], v[12:15]
	v_cndmask_b32_e64 v132, 1.0, v156, s[8:9]
	v_mul_f32_e32 v124, v132, v159
	v_pk_mul_f32 v[126:127], v[124:125], v[188:189] op_sel_hi:[0,1]
	v_mfma_f32_16x16x32_bf16 v[8:11], v[134:137], v[178:181], v[8:11]
	v_mul_f32_e64 v130, v124, v186
	v_mul_f32_e64 v131, v124, v187
	v_mfma_f32_16x16x32_bf16 v[4:7], v[160:163], v[178:181], v[4:7]
	v_mfma_f32_16x16x32_bf16 v[0:3], v[164:167], v[178:181], v[0:3]
	s_cbranch_vccz .LBB0_809
	v_mul_f32_e32 v125, 0xbfb8aa3b, v130
	v_exp_f32_e32 v125, v125
	v_mul_f32_e32 v133, 0xbfb8aa3b, v126
	v_mul_f32_e32 v128, 0xbfb8aa3b, v131
	v_exp_f32_e32 v128, v128
	v_add_f32_e32 v125, 1.0, v125
	v_rcp_f32_e32 v134, v125
	v_exp_f32_e32 v125, v133
	v_mul_f32_e32 v133, 0xbfb8aa3b, v127
	v_exp_f32_e32 v133, v133
	v_add_f32_e32 v128, 1.0, v128
	v_add_f32_e32 v125, 1.0, v125
	v_rcp_f32_e32 v136, v125
	v_add_f32_e32 v125, 1.0, v133
	v_rcp_f32_e32 v137, v125
	v_rcp_f32_e32 v135, v128
	v_pk_mul_f32 v[126:127], v[126:127], v[136:137]
	v_pk_mul_f32 v[130:131], v[130:131], v[134:135]

.Lgsk3_loop:
	s_add_i32 s8, s5, 0xfffe8000
	s_and_b32 s9, s5, 0x18000
	s_waitcnt vmcnt(8) lgkmcnt(0)
	s_barrier
	s_and_b32 s8, s8, 0x18000
	s_add_i32 s9, s4, s9
	v_add_u32_e32 v128, s8, v141
	v_or_b32_e32 v143, s8, v142
	s_add_i32 s11, s9, 0x400
	s_add_i32 s10, s9, 0x800
	s_add_i32 s8, s9, 0xc00
	s_add_i32 s5, s5, 0x8000
	s_cmp_eq_u32 s5, 0x100000
	ds_read_b128 v[174:177], v128
	ds_read_b128 v[178:181], v128 offset:1024
	ds_read_b128 v[182:185], v128 offset:2048
	ds_read_b128 v[186:189], v128 offset:3072
	v_mfma_f32_16x16x32_bf16 v[60:63], v[232:235], v[144:147], v[60:63]
	s_mov_b32 m0, s9
	v_mfma_f32_16x16x32_bf16 v[44:47], v[236:239], v[144:147], v[44:47]
	global_load_lds_dwordx4 v[136:137], off
	v_lshl_add_u64 v[136:137], v[136:137], 0, 64
	v_mfma_f32_16x16x32_bf16 v[28:31], v[240:243], v[144:147], v[28:31]
	s_mov_b32 m0, s11
	v_mfma_f32_16x16x32_bf16 v[12:15], v[244:247], v[144:147], v[12:15]
	global_load_lds_dwordx4 v[134:135], off
	v_lshl_add_u64 v[134:135], v[134:135], 0, 64
	v_mfma_f32_16x16x32_bf16 v[56:59], v[232:235], v[158:161], v[56:59]
	ds_read_b128 v[144:147], v143
	s_mov_b32 m0, s10
	v_mfma_f32_16x16x32_bf16 v[40:43], v[236:239], v[158:161], v[40:43]
	global_load_lds_dwordx4 v[132:133], off
	v_lshl_add_u64 v[132:133], v[132:133], 0, 64
	v_mfma_f32_16x16x32_bf16 v[24:27], v[240:243], v[158:161], v[24:27]
	s_mov_b32 m0, s8
	v_mfma_f32_16x16x32_bf16 v[8:11], v[244:247], v[158:161], v[8:11]
	global_load_lds_dwordx4 v[130:131], off
	v_lshl_add_u64 v[130:131], v[130:131], 0, 64
	v_mfma_f32_16x16x32_bf16 v[52:55], v[232:235], v[162:165], v[52:55]
	ds_read_b128 v[158:161], v143 offset:1024
	v_mfma_f32_16x16x32_bf16 v[36:39], v[236:239], v[162:165], v[36:39]
	v_mfma_f32_16x16x32_bf16 v[20:23], v[240:243], v[162:165], v[20:23]
	v_mfma_f32_16x16x32_bf16 v[4:7], v[244:247], v[162:165], v[4:7]
	v_mfma_f32_16x16x32_bf16 v[48:51], v[232:235], v[166:169], v[48:51]
	ds_read_b128 v[162:165], v143 offset:2048
	v_mfma_f32_16x16x32_bf16 v[32:35], v[236:239], v[166:169], v[32:35]
	v_mfma_f32_16x16x32_bf16 v[16:19], v[240:243], v[166:169], v[16:19]
	v_mfma_f32_16x16x32_bf16 v[0:3], v[244:247], v[166:169], v[0:3]
	s_waitcnt lgkmcnt(2)
	v_mfma_f32_16x16x32_bf16 v[124:127], v[174:177], v[144:147], v[124:127]
	ds_read_b128 v[166:169], v143 offset:3072
	v_mfma_f32_16x16x32_bf16 v[108:111], v[178:181], v[144:147], v[108:111]
	ds_read_b128 v[232:235], v128 offset:4096
	ds_read_b128 v[236:239], v128 offset:5120
	v_mfma_f32_16x16x32_bf16 v[92:95], v[182:185], v[144:147], v[92:95]
	ds_read_b128 v[240:243], v128 offset:6144
	ds_read_b128 v[244:247], v128 offset:7168
	v_mfma_f32_16x16x32_bf16 v[76:79], v[186:189], v[144:147], v[76:79]
	s_waitcnt lgkmcnt(6)
	v_mfma_f32_16x16x32_bf16 v[120:123], v[174:177], v[158:161], v[120:123]
	v_mfma_f32_16x16x32_bf16 v[104:107], v[178:181], v[158:161], v[104:107]
	v_mfma_f32_16x16x32_bf16 v[88:91], v[182:185], v[158:161], v[88:91]
	v_mfma_f32_16x16x32_bf16 v[72:75], v[186:189], v[158:161], v[72:75]
	s_waitcnt lgkmcnt(5)
	v_mfma_f32_16x16x32_bf16 v[116:119], v[174:177], v[162:165], v[116:119]
	v_mfma_f32_16x16x32_bf16 v[100:103], v[178:181], v[162:165], v[100:103]
	v_mfma_f32_16x16x32_bf16 v[84:87], v[182:185], v[162:165], v[84:87]
	v_mfma_f32_16x16x32_bf16 v[68:71], v[186:189], v[162:165], v[68:71]
	s_waitcnt lgkmcnt(4)
	v_mfma_f32_16x16x32_bf16 v[112:115], v[174:177], v[166:169], v[112:115]
	v_mfma_f32_16x16x32_bf16 v[96:99], v[178:181], v[166:169], v[96:99]
	v_mfma_f32_16x16x32_bf16 v[80:83], v[182:185], v[166:169], v[80:83]
	v_mfma_f32_16x16x32_bf16 v[64:67], v[186:189], v[166:169], v[64:67]
	s_cbranch_scc0 .Lgsk3_loop
	s_waitcnt lgkmcnt(0)
	v_mfma_f32_16x16x32_bf16 v[60:63], v[232:235], v[144:147], v[60:63]
	v_mfma_f32_16x16x32_bf16 v[44:47], v[236:239], v[144:147], v[44:47]
	v_mfma_f32_16x16x32_bf16 v[28:31], v[240:243], v[144:147], v[28:31]
	v_mfma_f32_16x16x32_bf16 v[12:15], v[244:247], v[144:147], v[12:15]
	v_mfma_f32_16x16x32_bf16 v[56:59], v[232:235], v[158:161], v[56:59]
	v_mfma_f32_16x16x32_bf16 v[40:43], v[236:239], v[158:161], v[40:43]
	v_mfma_f32_16x16x32_bf16 v[24:27], v[240:243], v[158:161], v[24:27]
	v_mfma_f32_16x16x32_bf16 v[8:11], v[244:247], v[158:161], v[8:11]
	v_mfma_f32_16x16x32_bf16 v[52:55], v[232:235], v[162:165], v[52:55]
	v_mfma_f32_16x16x32_bf16 v[36:39], v[236:239], v[162:165], v[36:39]
	v_mfma_f32_16x16x32_bf16 v[20:23], v[240:243], v[162:165], v[20:23]
	v_mfma_f32_16x16x32_bf16 v[4:7], v[244:247], v[162:165], v[4:7]
	v_mfma_f32_16x16x32_bf16 v[48:51], v[232:235], v[166:169], v[48:51]
	v_mfma_f32_16x16x32_bf16 v[32:35], v[236:239], v[166:169], v[32:35]
	v_mfma_f32_16x16x32_bf16 v[16:19], v[240:243], v[166:169], v[16:19]
	v_mfma_f32_16x16x32_bf16 v[0:3], v[244:247], v[166:169], v[0:3]
	s_waitcnt vmcnt(8)
	s_barrier
	v_add_u32_e32 v128, 0x8000, v141
	v_or_b32_e32 v143, 0x8000, v142
	ds_read_b128 v[130:133], v143
	ds_read_b128 v[134:137], v143 offset:1024
	ds_read_b128 v[144:147], v143 offset:2048
	ds_read_b128 v[158:161], v143 offset:3072
	ds_read_b128 v[162:165], v128
	ds_read_b128 v[166:169], v128 offset:1024
	ds_read_b128 v[174:177], v128 offset:2048
	ds_read_b128 v[178:181], v128 offset:3072
	v_or_b32_e32 v143, 0x10000, v142
	s_waitcnt lgkmcnt(0)
	s_ashr_i32 s13, s12, 31
	v_mfma_f32_16x16x32_bf16 v[124:127], v[162:165], v[130:133], v[124:127]
	s_lshl_b64 s[4:5], s[12:13], 2
	s_add_u32 s4, s62, s4
	s_addc_u32 s5, s63, s5
	v_mfma_f32_16x16x32_bf16 v[120:123], v[162:165], v[134:137], v[120:123]
	v_mfma_f32_16x16x32_bf16 v[116:119], v[162:165], v[144:147], v[116:119]
	v_mfma_f32_16x16x32_bf16 v[112:115], v[162:165], v[158:161], v[112:115]
	v_mfma_f32_16x16x32_bf16 v[108:111], v[166:169], v[130:133], v[108:111]
	v_mfma_f32_16x16x32_bf16 v[104:107], v[166:169], v[134:137], v[104:107]
	v_mfma_f32_16x16x32_bf16 v[100:103], v[166:169], v[144:147], v[100:103]
	v_mfma_f32_16x16x32_bf16 v[96:99], v[166:169], v[158:161], v[96:99]
	v_mfma_f32_16x16x32_bf16 v[92:95], v[174:177], v[130:133], v[92:95]
	v_mfma_f32_16x16x32_bf16 v[88:91], v[174:177], v[134:137], v[88:91]
	v_mfma_f32_16x16x32_bf16 v[84:87], v[174:177], v[144:147], v[84:87]
	v_mfma_f32_16x16x32_bf16 v[80:83], v[174:177], v[158:161], v[80:83]
	v_mfma_f32_16x16x32_bf16 v[76:79], v[178:181], v[130:133], v[76:79]
	v_mfma_f32_16x16x32_bf16 v[72:75], v[178:181], v[134:137], v[72:75]
	v_mfma_f32_16x16x32_bf16 v[68:71], v[178:181], v[144:147], v[68:71]
	v_mfma_f32_16x16x32_bf16 v[64:67], v[178:181], v[158:161], v[64:67]
	ds_read_b128 v[162:165], v128 offset:4096
	ds_read_b128 v[166:169], v128 offset:5120
	ds_read_b128 v[174:177], v128 offset:6144
	ds_read_b128 v[178:181], v128 offset:7168
	s_waitcnt lgkmcnt(0)
	s_waitcnt vmcnt(4)
	s_barrier
	v_mfma_f32_16x16x32_bf16 v[60:63], v[162:165], v[130:133], v[60:63]
	v_add_u32_e32 v128, 0x10000, v141
	v_mfma_f32_16x16x32_bf16 v[56:59], v[162:165], v[134:137], v[56:59]
	v_mfma_f32_16x16x32_bf16 v[52:55], v[162:165], v[144:147], v[52:55]
	v_mfma_f32_16x16x32_bf16 v[48:51], v[162:165], v[158:161], v[48:51]
	v_mfma_f32_16x16x32_bf16 v[44:47], v[166:169], v[130:133], v[44:47]
	v_mfma_f32_16x16x32_bf16 v[40:43], v[166:169], v[134:137], v[40:43]
	v_mfma_f32_16x16x32_bf16 v[36:39], v[166:169], v[144:147], v[36:39]
	v_mfma_f32_16x16x32_bf16 v[32:35], v[166:169], v[158:161], v[32:35]
	v_mfma_f32_16x16x32_bf16 v[28:31], v[174:177], v[130:133], v[28:31]
	v_mfma_f32_16x16x32_bf16 v[24:27], v[174:177], v[134:137], v[24:27]
	v_mfma_f32_16x16x32_bf16 v[20:23], v[174:177], v[144:147], v[20:23]
	v_mfma_f32_16x16x32_bf16 v[16:19], v[174:177], v[158:161], v[16:19]
	v_mfma_f32_16x16x32_bf16 v[12:15], v[178:181], v[130:133], v[12:15]
	v_mfma_f32_16x16x32_bf16 v[8:11], v[178:181], v[134:137], v[8:11]
	v_mfma_f32_16x16x32_bf16 v[4:7], v[178:181], v[144:147], v[4:7]
	v_mfma_f32_16x16x32_bf16 v[0:3], v[178:181], v[158:161], v[0:3]
	ds_read_b128 v[130:133], v143
	ds_read_b128 v[134:137], v143 offset:1024
	ds_read_b128 v[144:147], v143 offset:2048
	ds_read_b128 v[158:161], v143 offset:3072
	ds_read_b128 v[162:165], v128
	ds_read_b128 v[166:169], v128 offset:1024
	ds_read_b128 v[174:177], v128 offset:2048
	ds_read_b128 v[178:181], v128 offset:3072
	s_nop 0
	s_waitcnt lgkmcnt(0)
	s_nop 0
	v_mfma_f32_16x16x32_bf16 v[124:127], v[162:165], v[130:133], v[124:127]
	v_mfma_f32_16x16x32_bf16 v[120:123], v[162:165], v[134:137], v[120:123]
	v_mfma_f32_16x16x32_bf16 v[116:119], v[162:165], v[144:147], v[116:119]
	v_mfma_f32_16x16x32_bf16 v[112:115], v[162:165], v[158:161], v[112:115]
	v_mfma_f32_16x16x32_bf16 v[108:111], v[166:169], v[130:133], v[108:111]
	v_mfma_f32_16x16x32_bf16 v[104:107], v[166:169], v[134:137], v[104:107]
	v_mfma_f32_16x16x32_bf16 v[100:103], v[166:169], v[144:147], v[100:103]
	v_mfma_f32_16x16x32_bf16 v[96:99], v[166:169], v[158:161], v[96:99]
	v_mfma_f32_16x16x32_bf16 v[92:95], v[174:177], v[130:133], v[92:95]
	v_mfma_f32_16x16x32_bf16 v[88:91], v[174:177], v[134:137], v[88:91]
	v_mfma_f32_16x16x32_bf16 v[84:87], v[174:177], v[144:147], v[84:87]
	v_mfma_f32_16x16x32_bf16 v[80:83], v[174:177], v[158:161], v[80:83]
	v_mfma_f32_16x16x32_bf16 v[76:79], v[178:181], v[130:133], v[76:79]
	v_mfma_f32_16x16x32_bf16 v[72:75], v[178:181], v[134:137], v[72:75]
	v_mfma_f32_16x16x32_bf16 v[68:71], v[178:181], v[144:147], v[68:71]
	v_mfma_f32_16x16x32_bf16 v[64:67], v[178:181], v[158:161], v[64:67]
	ds_read_b128 v[162:165], v128 offset:4096
	ds_read_b128 v[166:169], v128 offset:5120
	ds_read_b128 v[174:177], v128 offset:6144
	ds_read_b128 v[178:181], v128 offset:7168
	s_waitcnt lgkmcnt(0)
	s_waitcnt vmcnt(0)
	s_barrier
	v_mfma_f32_16x16x32_bf16 v[60:63], v[162:165], v[130:133], v[60:63]
	v_add_u32_e32 v128, 0x18000, v141
	v_or_b32_e32 v141, 0x18000, v142
	v_mfma_f32_16x16x32_bf16 v[56:59], v[162:165], v[134:137], v[56:59]
	v_mfma_f32_16x16x32_bf16 v[52:55], v[162:165], v[144:147], v[52:55]
	v_mfma_f32_16x16x32_bf16 v[48:51], v[162:165], v[158:161], v[48:51]
	v_mfma_f32_16x16x32_bf16 v[44:47], v[166:169], v[130:133], v[44:47]
	v_mfma_f32_16x16x32_bf16 v[40:43], v[166:169], v[134:137], v[40:43]
	v_mfma_f32_16x16x32_bf16 v[36:39], v[166:169], v[144:147], v[36:39]
	v_mfma_f32_16x16x32_bf16 v[32:35], v[166:169], v[158:161], v[32:35]
	v_mfma_f32_16x16x32_bf16 v[28:31], v[174:177], v[130:133], v[28:31]
	v_mfma_f32_16x16x32_bf16 v[24:27], v[174:177], v[134:137], v[24:27]
	v_mfma_f32_16x16x32_bf16 v[20:23], v[174:177], v[144:147], v[20:23]
	v_mfma_f32_16x16x32_bf16 v[16:19], v[174:177], v[158:161], v[16:19]
	v_mfma_f32_16x16x32_bf16 v[12:15], v[178:181], v[130:133], v[12:15]
	v_mfma_f32_16x16x32_bf16 v[8:11], v[178:181], v[134:137], v[8:11]
	v_mfma_f32_16x16x32_bf16 v[4:7], v[178:181], v[144:147], v[4:7]
	v_mfma_f32_16x16x32_bf16 v[0:3], v[178:181], v[158:161], v[0:3]
	ds_read_b128 v[130:133], v141
	ds_read_b128 v[134:137], v141 offset:1024
	ds_read_b128 v[142:145], v141 offset:2048
	ds_read_b128 v[158:161], v141 offset:3072
	ds_read_b128 v[162:165], v128
	ds_read_b128 v[166:169], v128 offset:1024
	ds_read_b128 v[174:177], v128 offset:2048
	ds_read_b128 v[178:181], v128 offset:3072
	s_nop 0
	s_waitcnt lgkmcnt(0)
	s_nop 0
	v_mfma_f32_16x16x32_bf16 v[124:127], v[162:165], v[130:133], v[124:127]
	v_mfma_f32_16x16x32_bf16 v[120:123], v[162:165], v[134:137], v[120:123]
	v_mfma_f32_16x16x32_bf16 v[116:119], v[162:165], v[142:145], v[116:119]
	v_mfma_f32_16x16x32_bf16 v[162:165], v[162:165], v[158:161], v[112:115]
	v_mfma_f32_16x16x32_bf16 v[108:111], v[166:169], v[130:133], v[108:111]
	v_mfma_f32_16x16x32_bf16 v[104:107], v[166:169], v[134:137], v[104:107]
	v_mfma_f32_16x16x32_bf16 v[100:103], v[166:169], v[142:145], v[100:103]
	v_mfma_f32_16x16x32_bf16 v[96:99], v[166:169], v[158:161], v[96:99]
	v_mfma_f32_16x16x32_bf16 v[92:95], v[174:177], v[130:133], v[92:95]
	v_mfma_f32_16x16x32_bf16 v[88:91], v[174:177], v[134:137], v[88:91]
	v_mfma_f32_16x16x32_bf16 v[84:87], v[174:177], v[142:145], v[84:87]
	v_mfma_f32_16x16x32_bf16 v[80:83], v[174:177], v[158:161], v[80:83]
	v_mfma_f32_16x16x32_bf16 v[76:79], v[178:181], v[130:133], v[76:79]
	v_mfma_f32_16x16x32_bf16 v[72:75], v[178:181], v[134:137], v[72:75]
	v_mfma_f32_16x16x32_bf16 v[68:71], v[178:181], v[142:145], v[68:71]
	v_mfma_f32_16x16x32_bf16 v[64:67], v[178:181], v[158:161], v[64:67]
	ds_read_b128 v[112:115], v128 offset:4096
	ds_read_b128 v[166:169], v128 offset:5120
	ds_read_b128 v[174:177], v128 offset:6144
	ds_read_b128 v[178:181], v128 offset:7168
	s_waitcnt lgkmcnt(0)
	s_barrier
	v_mfma_f32_16x16x32_bf16 v[60:63], v[112:115], v[130:133], v[60:63]
	v_mfma_f32_16x16x32_bf16 v[56:59], v[112:115], v[134:137], v[56:59]
	v_mfma_f32_16x16x32_bf16 v[52:55], v[112:115], v[142:145], v[52:55]
	v_mfma_f32_16x16x32_bf16 v[48:51], v[112:115], v[158:161], v[48:51]
	v_lshlrev_b32_e32 v114, 3, v139
	v_lshlrev_b32_e32 v113, 8, v140
	v_and_b32_e32 v114, 8, v114
	v_add3_u32 v113, s38, v113, v114
	v_lshlrev_b32_e32 v114, 4, v139
	v_mfma_f32_16x16x32_bf16 v[44:47], v[166:169], v[130:133], v[44:47]
	v_lshrrev_b32_e32 v112, 5, v138
	v_xor_b32_e32 v115, v112, v140
	v_lshl_add_u32 v115, v115, 4, v113
	v_mfma_f32_16x16x32_bf16 v[28:31], v[174:177], v[130:133], v[28:31]
	v_mfma_f32_16x16x32_bf16 v[12:15], v[178:181], v[130:133], v[12:15]
	global_load_dwordx4 v[130:133], v114, s[4:5]
	s_waitcnt vmcnt(0)
	v_pk_mul_f32 v[126:127], v[126:127], v[132:133]
	v_pk_mul_f32 v[124:125], v[124:125], v[130:131]
	v_pk_mul_f32 v[122:123], v[122:123], v[132:133]
	v_pk_mul_f32 v[120:121], v[120:121], v[130:131]
	v_cvt_pk_bf16_f32 v124, v124, v125
	v_cvt_pk_bf16_f32 v125, v126, v127
	v_cvt_pk_bf16_f32 v120, v120, v121
	v_cvt_pk_bf16_f32 v121, v122, v123
	v_pk_mul_f32 v[118:119], v[118:119], v[132:133]
	v_pk_mul_f32 v[116:117], v[116:117], v[130:131]
	ds_write2st64_b64 v115, v[124:125], v[120:121] offset1:8
	v_cvt_pk_bf16_f32 v116, v116, v117
	v_cvt_pk_bf16_f32 v117, v118, v119
	v_pk_mul_f32 v[118:119], v[164:165], v[132:133]
	v_pk_mul_f32 v[120:121], v[162:163], v[130:131]
	v_mfma_f32_16x16x32_bf16 v[36:39], v[166:169], v[142:145], v[36:39]
	v_cvt_pk_bf16_f32 v120, v120, v121
	v_cvt_pk_bf16_f32 v121, v118, v119
	ds_write2st64_b64 v115, v[116:117], v[120:121] offset0:16 offset1:24
	global_load_dwordx4 v[116:119], v114, s[4:5] offset:64
	v_bitop3_b32 v115, v112, v140, 2 bitop3:0x36
	v_lshl_add_u32 v115, v115, 4, v113
	v_mfma_f32_16x16x32_bf16 v[32:35], v[166:169], v[158:161], v[32:35]
	s_waitcnt vmcnt(0)
	v_pk_mul_f32 v[102:103], v[102:103], v[118:119]
	v_pk_mul_f32 v[100:101], v[100:101], v[116:117]
	v_pk_mul_f32 v[98:99], v[98:99], v[118:119]
	v_pk_mul_f32 v[96:97], v[96:97], v[116:117]
	v_cvt_pk_bf16_f32 v100, v100, v101
	v_cvt_pk_bf16_f32 v101, v102, v103
	v_cvt_pk_bf16_f32 v96, v96, v97
	v_cvt_pk_bf16_f32 v97, v98, v99
	ds_write2st64_b64 v115, v[100:101], v[96:97] offset0:16 offset1:24
	global_load_dwordx4 v[96:99], v114, s[4:5] offset:128
	v_bitop3_b32 v100, v112, v140, 4 bitop3:0x36
	v_lshl_add_u32 v100, v100, 4, v113
	v_mfma_f32_16x16x32_bf16 v[20:23], v[174:177], v[142:145], v[20:23]
	v_mul_f32_e64 v110, v110, v118
	v_mul_f32_e64 v111, v111, v119
	v_pk_mul_f32 v[108:109], v[108:109], v[116:117]
	v_pk_mul_f32 v[106:107], v[106:107], v[118:119]
	v_mfma_f32_16x16x32_bf16 v[16:19], v[174:177], v[158:161], v[16:19]
	v_mul_f32_e64 v104, v104, v116
	v_mul_f32_e64 v105, v105, v117
	v_cvt_pk_bf16_f32 v108, v108, v109
	v_cvt_pk_bf16_f32 v109, v110, v111
	v_mfma_f32_16x16x32_bf16 v[0:3], v[178:181], v[158:161], v[0:3]
	v_cvt_pk_bf16_f32 v104, v104, v105
	v_cvt_pk_bf16_f32 v105, v106, v107
	ds_write2st64_b64 v115, v[108:109], v[104:105] offset1:8
	v_mfma_f32_16x16x32_bf16 v[8:11], v[178:181], v[134:137], v[8:11]
	s_waitcnt vmcnt(0)
	v_pk_mul_f32 v[86:87], v[86:87], v[98:99]
	v_pk_mul_f32 v[84:85], v[84:85], v[96:97]
	v_pk_mul_f32 v[82:83], v[82:83], v[98:99]
	v_pk_mul_f32 v[80:81], v[80:81], v[96:97]
	v_cvt_pk_bf16_f32 v84, v84, v85
	v_cvt_pk_bf16_f32 v85, v86, v87
	v_cvt_pk_bf16_f32 v80, v80, v81
	v_cvt_pk_bf16_f32 v81, v82, v83
	ds_write2st64_b64 v100, v[84:85], v[80:81] offset0:16 offset1:24
	global_load_dwordx4 v[80:83], v114, s[4:5] offset:192
	v_bitop3_b32 v84, v112, v140, 6 bitop3:0x36
	v_lshl_add_u32 v84, v84, 4, v113
	v_mfma_f32_16x16x32_bf16 v[40:43], v[166:169], v[134:137], v[40:43]
	v_mul_f32_e64 v94, v94, v98
	v_mul_f32_e64 v95, v95, v99
	v_pk_mul_f32 v[92:93], v[92:93], v[96:97]
	v_pk_mul_f32 v[90:91], v[90:91], v[98:99]
	v_mfma_f32_16x16x32_bf16 v[24:27], v[174:177], v[134:137], v[24:27]
	v_mul_f32_e64 v88, v88, v96
	v_mul_f32_e64 v89, v89, v97
	v_cvt_pk_bf16_f32 v92, v92, v93
	v_cvt_pk_bf16_f32 v93, v94, v95
	v_mfma_f32_16x16x32_bf16 v[4:7], v[178:181], v[142:145], v[4:7]
	v_cvt_pk_bf16_f32 v88, v88, v89
	v_cvt_pk_bf16_f32 v89, v90, v91
	ds_write2st64_b64 v100, v[92:93], v[88:89] offset1:8
	s_waitcnt vmcnt(0)
	v_pk_mul_f32 v[70:71], v[70:71], v[82:83]
	v_pk_mul_f32 v[68:69], v[68:69], v[80:81]
	v_pk_mul_f32 v[66:67], v[66:67], v[82:83]
	v_pk_mul_f32 v[64:65], v[64:65], v[80:81]
	v_cvt_pk_bf16_f32 v68, v68, v69
	v_cvt_pk_bf16_f32 v69, v70, v71
	v_cvt_pk_bf16_f32 v64, v64, v65
	v_cvt_pk_bf16_f32 v65, v66, v67
	ds_write2st64_b64 v84, v[68:69], v[64:65] offset0:16 offset1:24
	global_load_dwordx4 v[64:67], v114, s[4:5] offset:256
	v_bitop3_b32 v68, v112, v140, 8 bitop3:0x36
	v_lshl_add_u32 v68, v68, 4, v113
	v_pk_mul_f32 v[78:79], v[78:79], v[82:83]
	v_pk_mul_f32 v[76:77], v[76:77], v[80:81]
	v_pk_mul_f32 v[74:75], v[74:75], v[82:83]
	v_pk_mul_f32 v[72:73], v[72:73], v[80:81]
	v_cvt_pk_bf16_f32 v76, v76, v77
	v_cvt_pk_bf16_f32 v77, v78, v79
	v_cvt_pk_bf16_f32 v72, v72, v73
	v_cvt_pk_bf16_f32 v73, v74, v75
	ds_write2st64_b64 v84, v[76:77], v[72:73] offset1:8
	s_waitcnt vmcnt(0)
	v_pk_mul_f32 v[54:55], v[54:55], v[66:67]
	v_pk_mul_f32 v[52:53], v[52:53], v[64:65]
	v_pk_mul_f32 v[50:51], v[50:51], v[66:67]
	v_pk_mul_f32 v[48:49], v[48:49], v[64:65]
	v_cvt_pk_bf16_f32 v52, v52, v53
	v_cvt_pk_bf16_f32 v53, v54, v55
	v_cvt_pk_bf16_f32 v48, v48, v49
	v_cvt_pk_bf16_f32 v49, v50, v51
	ds_write2st64_b64 v68, v[52:53], v[48:49] offset0:16 offset1:24
	global_load_dwordx4 v[48:51], v114, s[4:5] offset:320
	v_bitop3_b32 v52, v112, v140, 10 bitop3:0x36
	v_lshl_add_u32 v52, v52, 4, v113
	v_pk_mul_f32 v[62:63], v[62:63], v[66:67]
	v_pk_mul_f32 v[60:61], v[60:61], v[64:65]
	v_pk_mul_f32 v[58:59], v[58:59], v[66:67]
	v_pk_mul_f32 v[56:57], v[56:57], v[64:65]
	v_cvt_pk_bf16_f32 v60, v60, v61
	v_cvt_pk_bf16_f32 v61, v62, v63
	v_cvt_pk_bf16_f32 v56, v56, v57
	v_cvt_pk_bf16_f32 v57, v58, v59
	ds_write2st64_b64 v68, v[60:61], v[56:57] offset1:8
	s_waitcnt vmcnt(0)
	v_pk_mul_f32 v[38:39], v[38:39], v[50:51]
	v_pk_mul_f32 v[36:37], v[36:37], v[48:49]
	v_pk_mul_f32 v[34:35], v[34:35], v[50:51]
	v_pk_mul_f32 v[32:33], v[32:33], v[48:49]
	v_cvt_pk_bf16_f32 v36, v36, v37
	v_cvt_pk_bf16_f32 v37, v38, v39
	v_cvt_pk_bf16_f32 v32, v32, v33
	v_cvt_pk_bf16_f32 v33, v34, v35
	ds_write2st64_b64 v52, v[36:37], v[32:33] offset0:16 offset1:24
	global_load_dwordx4 v[32:35], v114, s[4:5] offset:384
	v_bitop3_b32 v36, v112, v140, 12 bitop3:0x36
	v_lshl_add_u32 v36, v36, 4, v113
	v_pk_mul_f32 v[46:47], v[46:47], v[50:51]
	v_pk_mul_f32 v[44:45], v[44:45], v[48:49]
	v_pk_mul_f32 v[42:43], v[42:43], v[50:51]
	v_pk_mul_f32 v[40:41], v[40:41], v[48:49]
	v_cvt_pk_bf16_f32 v44, v44, v45
	v_cvt_pk_bf16_f32 v45, v46, v47
	v_cvt_pk_bf16_f32 v40, v40, v41
	v_cvt_pk_bf16_f32 v41, v42, v43
	ds_write2st64_b64 v52, v[44:45], v[40:41] offset1:8
	s_waitcnt vmcnt(0)
	v_pk_mul_f32 v[22:23], v[22:23], v[34:35]
	v_pk_mul_f32 v[20:21], v[20:21], v[32:33]
	v_pk_mul_f32 v[18:19], v[18:19], v[34:35]
	v_pk_mul_f32 v[16:17], v[16:17], v[32:33]
	v_cvt_pk_bf16_f32 v20, v20, v21
	v_cvt_pk_bf16_f32 v21, v22, v23
	v_cvt_pk_bf16_f32 v16, v16, v17
	v_cvt_pk_bf16_f32 v17, v18, v19
	ds_write2st64_b64 v36, v[20:21], v[16:17] offset0:16 offset1:24
	global_load_dwordx4 v[16:19], v114, s[4:5] offset:448
	s_lshr_b32 s4, s40, 6
	s_and_b32 s5, s39, -16
	s_or_b32 s4, s4, s5
	v_bitop3_b32 v20, v112, v140, 14 bitop3:0x36
	s_ashr_i32 s5, s4, 31
	v_pk_mul_f32 v[30:31], v[30:31], v[34:35]
	v_pk_mul_f32 v[28:29], v[28:29], v[32:33]
	v_pk_mul_f32 v[26:27], v[26:27], v[34:35]
	v_pk_mul_f32 v[24:25], v[24:25], v[32:33]
	v_lshl_add_u32 v20, v20, 4, v113
	s_lshl_b64 s[4:5], s[4:5], 19
	v_cvt_pk_bf16_f32 v28, v28, v29
	v_cvt_pk_bf16_f32 v29, v30, v31
	v_cvt_pk_bf16_f32 v24, v24, v25
	v_cvt_pk_bf16_f32 v25, v26, v27
	s_add_u32 s4, s26, s4
	ds_write2st64_b64 v36, v[28:29], v[24:25] offset1:8
	s_addc_u32 s5, s27, s5
	s_and_b32 s8, s12, 0xf80
	s_lshl_b32 s8, s8, 1
	s_add_u32 s4, s4, s8
	s_addc_u32 s5, s5, 0
	s_waitcnt vmcnt(0)
	v_pk_mul_f32 v[2:3], v[2:3], v[18:19]
	v_pk_mul_f32 v[0:1], v[0:1], v[16:17]
	v_pk_mul_f32 v[14:15], v[14:15], v[18:19]
	v_pk_mul_f32 v[12:13], v[12:13], v[16:17]
	v_pk_mul_f32 v[10:11], v[10:11], v[18:19]
	v_pk_mul_f32 v[8:9], v[8:9], v[16:17]
	v_cvt_pk_bf16_f32 v0, v0, v1
	v_cvt_pk_bf16_f32 v1, v2, v3
	v_xor_b32_e32 v3, v139, v138
	v_cvt_pk_bf16_f32 v12, v12, v13
	v_cvt_pk_bf16_f32 v13, v14, v15
	v_cvt_pk_bf16_f32 v8, v8, v9
	v_cvt_pk_bf16_f32 v9, v10, v11
	v_lshlrev_b32_e32 v3, 4, v3
	ds_write2st64_b64 v20, v[12:13], v[8:9] offset1:8
	v_pk_mul_f32 v[6:7], v[6:7], v[18:19]
	v_pk_mul_f32 v[4:5], v[4:5], v[16:17]
	v_lshlrev_b32_e32 v2, 8, v139
	v_and_b32_e32 v8, 0xf0, v3
	v_cvt_pk_bf16_f32 v4, v4, v5
	v_cvt_pk_bf16_f32 v5, v6, v7
	v_add3_u32 v2, s38, v2, v8
	ds_write2st64_b64 v20, v[4:5], v[0:1] offset0:16 offset1:24
	ds_read_b128 v[2:5], v2
	v_lshlrev_b32_e32 v0, 4, v138
	v_and_b32_e32 v128, 0xf0, v0
	v_lshl_add_u64 v[0:1], s[4:5], 0, v[128:129]
	v_lshlrev_b32_e32 v128, 13, v139
	v_lshl_add_u64 v[6:7], v[0:1], 0, v[128:129]
	s_waitcnt lgkmcnt(0)
	global_store_dwordx4 v[6:7], v[2:5], off
	v_or_b32_e32 v6, 4, v139
	v_lshlrev_b32_e32 v128, 13, v6
	v_bitop3_b32 v3, v139, v138, 4 bitop3:0x36
	v_lshlrev_b32_e32 v3, 4, v3
	v_lshlrev_b32_e32 v2, 8, v6
	v_and_b32_e32 v3, 0xf0, v3
	v_add3_u32 v2, s38, v2, v3
	ds_read_b128 v[2:5], v2
	v_lshl_add_u64 v[6:7], v[0:1], 0, v[128:129]
	s_waitcnt lgkmcnt(0)
	global_store_dwordx4 v[6:7], v[2:5], off
	s_nop 1
	v_bitop3_b32 v3, v139, v138, 8 bitop3:0x36
	v_or_b32_e32 v6, 8, v139
	v_lshlrev_b32_e32 v3, 4, v3
	v_lshlrev_b32_e32 v2, 8, v6
	v_and_b32_e32 v3, 0xf0, v3
	v_add3_u32 v2, s38, v2, v3
	ds_read_b128 v[2:5], v2
	v_lshlrev_b32_e32 v128, 13, v6
	v_lshl_add_u64 v[6:7], v[0:1], 0, v[128:129]
	s_waitcnt lgkmcnt(0)
	global_store_dwordx4 v[6:7], v[2:5], off
	s_nop 1
	v_bitop3_b32 v3, v139, v138, 12 bitop3:0x36
	v_or_b32_e32 v6, 12, v139
	v_lshlrev_b32_e32 v3, 4, v3
	v_lshlrev_b32_e32 v2, 8, v6
	v_and_b32_e32 v3, 0xf0, v3
	v_add3_u32 v2, s38, v2, v3
	ds_read_b128 v[2:5], v2
	v_lshlrev_b32_e32 v128, 13, v6
	v_lshl_add_u64 v[6:7], v[0:1], 0, v[128:129]
	s_waitcnt lgkmcnt(0)
	global_store_dwordx4 v[6:7], v[2:5], off
	v_or_b32_e32 v6, 16, v139
	s_nop 0
	v_lshlrev_b32_e32 v2, 8, v6
	v_add3_u32 v2, s38, v2, v8
	ds_read_b128 v[2:5], v2
	v_lshlrev_b32_e32 v128, 13, v6
	v_lshl_add_u64 v[6:7], v[0:1], 0, v[128:129]
	s_waitcnt lgkmcnt(0)
	global_store_dwordx4 v[6:7], v[2:5], off
	s_nop 1
	v_bitop3_b32 v3, v139, v138, 20 bitop3:0x36
	v_or_b32_e32 v6, 20, v139
	v_lshlrev_b32_e32 v3, 4, v3
	v_lshlrev_b32_e32 v2, 8, v6
	v_and_b32_e32 v3, 0xf0, v3
	v_add3_u32 v2, s38, v2, v3
	ds_read_b128 v[2:5], v2
	v_lshlrev_b32_e32 v128, 13, v6
	v_lshl_add_u64 v[6:7], v[0:1], 0, v[128:129]
	s_waitcnt lgkmcnt(0)
	global_store_dwordx4 v[6:7], v[2:5], off
	s_nop 1
	v_bitop3_b32 v3, v139, v138, 24 bitop3:0x36
	v_or_b32_e32 v6, 24, v139
	v_lshlrev_b32_e32 v3, 4, v3
	v_lshlrev_b32_e32 v2, 8, v6
	v_and_b32_e32 v3, 0xf0, v3
	v_add3_u32 v2, s38, v2, v3
	ds_read_b128 v[2:5], v2
	v_lshlrev_b32_e32 v128, 13, v6
	v_lshl_add_u64 v[6:7], v[0:1], 0, v[128:129]
	s_waitcnt lgkmcnt(0)
	global_store_dwordx4 v[6:7], v[2:5], off
	s_nop 1
	v_bitop3_b32 v3, v139, v138, 28 bitop3:0x36
	v_or_b32_e32 v6, 28, v139
	v_lshlrev_b32_e32 v3, 4, v3
	v_lshlrev_b32_e32 v2, 8, v6
	v_and_b32_e32 v3, 0xf0, v3
	v_add3_u32 v2, s38, v2, v3
	ds_read_b128 v[2:5], v2
	v_lshlrev_b32_e32 v128, 13, v6
	v_lshl_add_u64 v[6:7], v[0:1], 0, v[128:129]
	s_waitcnt lgkmcnt(0)
	global_store_dwordx4 v[6:7], v[2:5], off
	v_or_b32_e32 v6, 32, v139
	s_nop 0
	v_lshlrev_b32_e32 v2, 8, v6
	v_add3_u32 v2, s38, v2, v8
	ds_read_b128 v[2:5], v2
	v_lshlrev_b32_e32 v128, 13, v6
	v_lshl_add_u64 v[6:7], v[0:1], 0, v[128:129]
	s_waitcnt lgkmcnt(0)
	global_store_dwordx4 v[6:7], v[2:5], off
	s_nop 1
	v_bitop3_b32 v3, v139, v138, 36 bitop3:0x36
	v_or_b32_e32 v6, 36, v139
	v_lshlrev_b32_e32 v3, 4, v3
	v_lshlrev_b32_e32 v2, 8, v6
	v_and_b32_e32 v3, 0xf0, v3
	v_add3_u32 v2, s38, v2, v3
	ds_read_b128 v[2:5], v2
	v_lshlrev_b32_e32 v128, 13, v6
	v_lshl_add_u64 v[6:7], v[0:1], 0, v[128:129]
	s_waitcnt lgkmcnt(0)
	global_store_dwordx4 v[6:7], v[2:5], off
	s_nop 1
	v_bitop3_b32 v3, v139, v138, 40 bitop3:0x36
	v_or_b32_e32 v6, 40, v139
	v_lshlrev_b32_e32 v3, 4, v3
	v_lshlrev_b32_e32 v2, 8, v6
	v_and_b32_e32 v3, 0xf0, v3
	v_add3_u32 v2, s38, v2, v3
	ds_read_b128 v[2:5], v2
	v_lshlrev_b32_e32 v128, 13, v6
	v_lshl_add_u64 v[6:7], v[0:1], 0, v[128:129]
	s_waitcnt lgkmcnt(0)
	global_store_dwordx4 v[6:7], v[2:5], off
	s_nop 1
	v_bitop3_b32 v3, v139, v138, 44 bitop3:0x36
	v_or_b32_e32 v6, 44, v139
	v_lshlrev_b32_e32 v3, 4, v3
	v_lshlrev_b32_e32 v2, 8, v6
	v_and_b32_e32 v3, 0xf0, v3
	v_add3_u32 v2, s38, v2, v3
	ds_read_b128 v[2:5], v2
	v_lshlrev_b32_e32 v128, 13, v6
	v_lshl_add_u64 v[6:7], v[0:1], 0, v[128:129]
	s_waitcnt lgkmcnt(0)
	global_store_dwordx4 v[6:7], v[2:5], off
	v_or_b32_e32 v6, 48, v139
	s_nop 0
	v_lshlrev_b32_e32 v2, 8, v6
	v_add3_u32 v2, s38, v2, v8
	ds_read_b128 v[2:5], v2
	v_lshlrev_b32_e32 v128, 13, v6
	v_lshl_add_u64 v[6:7], v[0:1], 0, v[128:129]
	s_waitcnt lgkmcnt(0)
	global_store_dwordx4 v[6:7], v[2:5], off
	s_nop 1
	v_bitop3_b32 v3, v139, v138, 52 bitop3:0x36
	v_or_b32_e32 v6, 52, v139
	v_lshlrev_b32_e32 v3, 4, v3
	v_lshlrev_b32_e32 v2, 8, v6
	v_and_b32_e32 v3, 0xf0, v3
	v_add3_u32 v2, s38, v2, v3
	ds_read_b128 v[2:5], v2
	v_lshlrev_b32_e32 v128, 13, v6
	v_lshl_add_u64 v[6:7], v[0:1], 0, v[128:129]
	s_waitcnt lgkmcnt(0)
	global_store_dwordx4 v[6:7], v[2:5], off
	s_nop 1
	v_bitop3_b32 v3, v139, v138, 56 bitop3:0x36
	v_or_b32_e32 v6, 56, v139
	v_lshlrev_b32_e32 v3, 4, v3
	v_lshlrev_b32_e32 v2, 8, v6
	v_and_b32_e32 v3, 0xf0, v3
	v_add3_u32 v2, s38, v2, v3
	ds_read_b128 v[2:5], v2
	v_lshlrev_b32_e32 v128, 13, v6
	v_lshl_add_u64 v[6:7], v[0:1], 0, v[128:129]
	s_waitcnt lgkmcnt(0)
	global_store_dwordx4 v[6:7], v[2:5], off
	s_nop 1
	v_bitop3_b32 v4, v139, v138, 60 bitop3:0x36
	v_or_b32_e32 v3, 60, v139
	v_lshlrev_b32_e32 v4, 4, v4
	v_lshlrev_b32_e32 v2, 8, v3
	v_and_b32_e32 v4, 0xf0, v4
	v_add3_u32 v2, s38, v2, v4
	v_lshlrev_b32_e32 v128, 12, v3
	s_branch .LBB0_803

.Lgsk4_loop:
	s_add_i32 s9, s8, 0xfffe8000
	s_and_b32 s10, s8, 0x18000
	s_waitcnt vmcnt(8) lgkmcnt(0)
	s_barrier
	s_and_b32 s9, s9, 0x18000
	s_add_i32 s10, s7, s10
	v_add_u32_e32 v128, s9, v139
	v_or_b32_e32 v141, s9, v140
	s_add_i32 s15, s10, 0x400
	s_add_i32 s11, s10, 0x800
	s_add_i32 s9, s10, 0xc00
	s_add_i32 s8, s8, 0x8000
	s_cmp_eq_u32 s8, 0x100000
	ds_read_b128 v[174:177], v128
	ds_read_b128 v[178:181], v128 offset:1024
	ds_read_b128 v[182:185], v128 offset:2048
	ds_read_b128 v[186:189], v128 offset:3072
	v_mfma_f32_16x16x32_bf16 v[60:63], v[142:145], v[232:235], v[60:63]
	s_mov_b32 m0, s10
	v_mfma_f32_16x16x32_bf16 v[44:47], v[142:145], v[236:239], v[44:47]
	global_load_lds_dwordx4 v[136:137], off
	v_lshl_add_u64 v[136:137], v[136:137], 0, 64
	v_mfma_f32_16x16x32_bf16 v[28:31], v[142:145], v[240:243], v[28:31]
	s_mov_b32 m0, s15
	v_mfma_f32_16x16x32_bf16 v[12:15], v[142:145], v[244:247], v[12:15]
	global_load_lds_dwordx4 v[134:135], off
	v_lshl_add_u64 v[134:135], v[134:135], 0, 64
	v_mfma_f32_16x16x32_bf16 v[56:59], v[158:161], v[232:235], v[56:59]
	ds_read_b128 v[142:145], v141
	s_mov_b32 m0, s11
	v_mfma_f32_16x16x32_bf16 v[40:43], v[158:161], v[236:239], v[40:43]
	global_load_lds_dwordx4 v[132:133], off
	v_lshl_add_u64 v[132:133], v[132:133], 0, 64
	v_mfma_f32_16x16x32_bf16 v[24:27], v[158:161], v[240:243], v[24:27]
	s_mov_b32 m0, s9
	v_mfma_f32_16x16x32_bf16 v[8:11], v[158:161], v[244:247], v[8:11]
	global_load_lds_dwordx4 v[130:131], off
	v_lshl_add_u64 v[130:131], v[130:131], 0, 64
	v_mfma_f32_16x16x32_bf16 v[52:55], v[162:165], v[232:235], v[52:55]
	ds_read_b128 v[158:161], v141 offset:1024
	v_mfma_f32_16x16x32_bf16 v[36:39], v[162:165], v[236:239], v[36:39]
	v_mfma_f32_16x16x32_bf16 v[20:23], v[162:165], v[240:243], v[20:23]
	v_mfma_f32_16x16x32_bf16 v[4:7], v[162:165], v[244:247], v[4:7]
	v_mfma_f32_16x16x32_bf16 v[48:51], v[166:169], v[232:235], v[48:51]
	ds_read_b128 v[162:165], v141 offset:2048
	v_mfma_f32_16x16x32_bf16 v[32:35], v[166:169], v[236:239], v[32:35]
	v_mfma_f32_16x16x32_bf16 v[16:19], v[166:169], v[240:243], v[16:19]
	v_mfma_f32_16x16x32_bf16 v[0:3], v[166:169], v[244:247], v[0:3]
	s_waitcnt lgkmcnt(2)
	v_mfma_f32_16x16x32_bf16 v[124:127], v[142:145], v[174:177], v[124:127]
	ds_read_b128 v[166:169], v141 offset:3072
	v_mfma_f32_16x16x32_bf16 v[108:111], v[142:145], v[178:181], v[108:111]
	ds_read_b128 v[232:235], v128 offset:4096
	ds_read_b128 v[236:239], v128 offset:5120
	v_mfma_f32_16x16x32_bf16 v[92:95], v[142:145], v[182:185], v[92:95]
	ds_read_b128 v[240:243], v128 offset:6144
	ds_read_b128 v[244:247], v128 offset:7168
	v_mfma_f32_16x16x32_bf16 v[76:79], v[142:145], v[186:189], v[76:79]
	s_waitcnt lgkmcnt(6)
	v_mfma_f32_16x16x32_bf16 v[120:123], v[158:161], v[174:177], v[120:123]
	v_mfma_f32_16x16x32_bf16 v[104:107], v[158:161], v[178:181], v[104:107]
	v_mfma_f32_16x16x32_bf16 v[88:91], v[158:161], v[182:185], v[88:91]
	v_mfma_f32_16x16x32_bf16 v[72:75], v[158:161], v[186:189], v[72:75]
	s_waitcnt lgkmcnt(5)
	v_mfma_f32_16x16x32_bf16 v[116:119], v[162:165], v[174:177], v[116:119]
	v_mfma_f32_16x16x32_bf16 v[100:103], v[162:165], v[178:181], v[100:103]
	v_mfma_f32_16x16x32_bf16 v[84:87], v[162:165], v[182:185], v[84:87]
	v_mfma_f32_16x16x32_bf16 v[68:71], v[162:165], v[186:189], v[68:71]
	s_waitcnt lgkmcnt(4)
	v_mfma_f32_16x16x32_bf16 v[112:115], v[166:169], v[174:177], v[112:115]
	v_mfma_f32_16x16x32_bf16 v[96:99], v[166:169], v[178:181], v[96:99]
	v_mfma_f32_16x16x32_bf16 v[80:83], v[166:169], v[182:185], v[80:83]
	v_mfma_f32_16x16x32_bf16 v[64:67], v[166:169], v[186:189], v[64:67]
	s_cbranch_scc0 .Lgsk4_loop
	s_waitcnt lgkmcnt(0)
	v_mfma_f32_16x16x32_bf16 v[60:63], v[142:145], v[232:235], v[60:63]
	v_mfma_f32_16x16x32_bf16 v[44:47], v[142:145], v[236:239], v[44:47]
	v_mfma_f32_16x16x32_bf16 v[28:31], v[142:145], v[240:243], v[28:31]
	v_mfma_f32_16x16x32_bf16 v[12:15], v[142:145], v[244:247], v[12:15]
	v_mfma_f32_16x16x32_bf16 v[56:59], v[158:161], v[232:235], v[56:59]
	v_mfma_f32_16x16x32_bf16 v[40:43], v[158:161], v[236:239], v[40:43]
	v_mfma_f32_16x16x32_bf16 v[24:27], v[158:161], v[240:243], v[24:27]
	v_mfma_f32_16x16x32_bf16 v[8:11], v[158:161], v[244:247], v[8:11]
	v_mfma_f32_16x16x32_bf16 v[52:55], v[162:165], v[232:235], v[52:55]
	v_mfma_f32_16x16x32_bf16 v[36:39], v[162:165], v[236:239], v[36:39]
	v_mfma_f32_16x16x32_bf16 v[20:23], v[162:165], v[240:243], v[20:23]
	v_mfma_f32_16x16x32_bf16 v[4:7], v[162:165], v[244:247], v[4:7]
	v_mfma_f32_16x16x32_bf16 v[48:51], v[166:169], v[232:235], v[48:51]
	v_mfma_f32_16x16x32_bf16 v[32:35], v[166:169], v[236:239], v[32:35]
	v_mfma_f32_16x16x32_bf16 v[16:19], v[166:169], v[240:243], v[16:19]
	v_mfma_f32_16x16x32_bf16 v[0:3], v[166:169], v[244:247], v[0:3]
	s_waitcnt vmcnt(8)
	s_barrier
	v_add_u32_e32 v128, 0x8000, v139
	v_or_b32_e32 v141, 0x8000, v140
	ds_read_b128 v[130:133], v141
	ds_read_b128 v[134:137], v141 offset:1024
	ds_read_b128 v[142:145], v141 offset:2048
	ds_read_b128 v[158:161], v141 offset:3072
	ds_read_b128 v[162:165], v128
	ds_read_b128 v[166:169], v128 offset:1024
	ds_read_b128 v[174:177], v128 offset:2048
	ds_read_b128 v[178:181], v128 offset:3072
	s_lshl_b32 s8, s6, 8
	s_waitcnt lgkmcnt(0)
	s_and_b32 s15, s8, 0xffffc000
	v_mfma_f32_16x16x32_bf16 v[124:127], v[130:133], v[162:165], v[124:127]
	s_ashr_i32 s7, s6, 1
	s_and_b32 s7, s7, 0xffffff80
	s_and_b32 s6, s6, 0xc0
	v_mfma_f32_16x16x32_bf16 v[120:123], v[134:137], v[162:165], v[120:123]
	s_add_i32 s8, s4, s7
	s_or_b32 s4, s5, s6
	s_ashr_i32 s10, s4, 6
	v_mfma_f32_16x16x32_bf16 v[182:185], v[142:145], v[162:165], v[116:119]
	s_ashr_i32 s11, s10, 31
	v_mfma_f32_16x16x32_bf16 v[112:115], v[158:161], v[162:165], v[112:115]
	v_mfma_f32_16x16x32_bf16 v[108:111], v[130:133], v[166:169], v[108:111]
	v_mfma_f32_16x16x32_bf16 v[104:107], v[134:137], v[166:169], v[104:107]
	v_mfma_f32_16x16x32_bf16 v[100:103], v[142:145], v[166:169], v[100:103]
	v_mfma_f32_16x16x32_bf16 v[96:99], v[158:161], v[166:169], v[96:99]
	v_mfma_f32_16x16x32_bf16 v[92:95], v[130:133], v[174:177], v[92:95]
	v_mfma_f32_16x16x32_bf16 v[88:91], v[134:137], v[174:177], v[88:91]
	v_mfma_f32_16x16x32_bf16 v[84:87], v[142:145], v[174:177], v[84:87]
	v_mfma_f32_16x16x32_bf16 v[80:83], v[158:161], v[174:177], v[80:83]
	ds_read_b128 v[116:119], v128 offset:4096
	ds_read_b128 v[162:165], v128 offset:5120
	ds_read_b128 v[166:169], v128 offset:6144
	ds_read_b128 v[174:177], v128 offset:7168
	s_waitcnt lgkmcnt(0)
	s_waitcnt vmcnt(4)
	s_barrier
	v_mfma_f32_16x16x32_bf16 v[76:79], v[130:133], v[178:181], v[76:79]
	v_mfma_f32_16x16x32_bf16 v[72:75], v[134:137], v[178:181], v[72:75]
	v_mfma_f32_16x16x32_bf16 v[68:71], v[142:145], v[178:181], v[68:71]
	v_mfma_f32_16x16x32_bf16 v[64:67], v[158:161], v[178:181], v[64:67]
	v_mfma_f32_16x16x32_bf16 v[60:63], v[130:133], v[116:119], v[60:63]
	v_mfma_f32_16x16x32_bf16 v[56:59], v[134:137], v[116:119], v[56:59]
	v_mfma_f32_16x16x32_bf16 v[52:55], v[142:145], v[116:119], v[52:55]
	v_mfma_f32_16x16x32_bf16 v[48:51], v[158:161], v[116:119], v[48:51]
	v_add_u32_e32 v117, 0x10000, v139
	v_or_b32_e32 v119, 0x10000, v140
	v_and_b32_e32 v116, 15, v138
	v_mfma_f32_16x16x32_bf16 v[44:47], v[130:133], v[162:165], v[44:47]
	v_and_b32_e32 v118, 63, v138
	v_mfma_f32_16x16x32_bf16 v[40:43], v[134:137], v[162:165], v[40:43]
	v_mfma_f32_16x16x32_bf16 v[36:39], v[142:145], v[162:165], v[36:39]
	v_mfma_f32_16x16x32_bf16 v[32:35], v[158:161], v[162:165], v[32:35]
	v_mfma_f32_16x16x32_bf16 v[28:31], v[130:133], v[166:169], v[28:31]
	v_mfma_f32_16x16x32_bf16 v[24:27], v[134:137], v[166:169], v[24:27]
	v_mfma_f32_16x16x32_bf16 v[20:23], v[142:145], v[166:169], v[20:23]
	v_mfma_f32_16x16x32_bf16 v[16:19], v[158:161], v[166:169], v[16:19]
	v_mfma_f32_16x16x32_bf16 v[12:15], v[130:133], v[174:177], v[12:15]
	v_mfma_f32_16x16x32_bf16 v[8:11], v[134:137], v[174:177], v[8:11]
	v_mfma_f32_16x16x32_bf16 v[4:7], v[142:145], v[174:177], v[4:7]
	v_mfma_f32_16x16x32_bf16 v[0:3], v[158:161], v[174:177], v[0:3]
	ds_read_b128 v[130:133], v119
	ds_read_b128 v[134:137], v119 offset:1024
	ds_read_b128 v[142:145], v119 offset:2048
	ds_read_b128 v[158:161], v119 offset:3072
	ds_read_b128 v[162:165], v117
	ds_read_b128 v[166:169], v117 offset:1024
	ds_read_b128 v[174:177], v117 offset:2048
	ds_read_b128 v[178:181], v117 offset:3072
	v_or_b32_e32 v119, 0x18000, v140
	s_waitcnt lgkmcnt(0)
	s_nop 0
	v_mfma_f32_16x16x32_bf16 v[124:127], v[130:133], v[162:165], v[124:127]
	v_mfma_f32_16x16x32_bf16 v[120:123], v[134:137], v[162:165], v[120:123]
	v_mfma_f32_16x16x32_bf16 v[182:185], v[142:145], v[162:165], v[182:185]
	v_mfma_f32_16x16x32_bf16 v[112:115], v[158:161], v[162:165], v[112:115]
	v_mfma_f32_16x16x32_bf16 v[108:111], v[130:133], v[166:169], v[108:111]
	v_mfma_f32_16x16x32_bf16 v[104:107], v[134:137], v[166:169], v[104:107]
	v_mfma_f32_16x16x32_bf16 v[100:103], v[142:145], v[166:169], v[100:103]
	v_mfma_f32_16x16x32_bf16 v[162:165], v[158:161], v[166:169], v[96:99]
	v_mfma_f32_16x16x32_bf16 v[92:95], v[130:133], v[174:177], v[92:95]
	v_mfma_f32_16x16x32_bf16 v[88:91], v[134:137], v[174:177], v[88:91]
	v_mfma_f32_16x16x32_bf16 v[84:87], v[142:145], v[174:177], v[84:87]
	v_mfma_f32_16x16x32_bf16 v[80:83], v[158:161], v[174:177], v[80:83]
	v_mfma_f32_16x16x32_bf16 v[76:79], v[130:133], v[178:181], v[76:79]
	v_mfma_f32_16x16x32_bf16 v[72:75], v[134:137], v[178:181], v[72:75]
	v_mfma_f32_16x16x32_bf16 v[68:71], v[142:145], v[178:181], v[68:71]
	v_mfma_f32_16x16x32_bf16 v[64:67], v[158:161], v[178:181], v[64:67]
	ds_read_b128 v[96:99], v117 offset:4096
	ds_read_b128 v[166:169], v117 offset:5120
	ds_read_b128 v[174:177], v117 offset:6144
	ds_read_b128 v[178:181], v117 offset:7168
	s_waitcnt lgkmcnt(0)
	s_waitcnt vmcnt(0)
	s_barrier
	v_mfma_f32_16x16x32_bf16 v[60:63], v[130:133], v[96:99], v[60:63]
	v_add_u32_e32 v117, 0x18000, v139
	v_mfma_f32_16x16x32_bf16 v[56:59], v[134:137], v[96:99], v[56:59]
	v_mfma_f32_16x16x32_bf16 v[52:55], v[142:145], v[96:99], v[52:55]
	v_mfma_f32_16x16x32_bf16 v[48:51], v[158:161], v[96:99], v[48:51]
	v_mfma_f32_16x16x32_bf16 v[44:47], v[130:133], v[166:169], v[44:47]
	v_mfma_f32_16x16x32_bf16 v[40:43], v[134:137], v[166:169], v[40:43]
	v_mfma_f32_16x16x32_bf16 v[36:39], v[142:145], v[166:169], v[36:39]
	v_mfma_f32_16x16x32_bf16 v[32:35], v[158:161], v[166:169], v[32:35]
	v_mfma_f32_16x16x32_bf16 v[28:31], v[130:133], v[174:177], v[28:31]
	v_mfma_f32_16x16x32_bf16 v[24:27], v[134:137], v[174:177], v[24:27]
	v_mfma_f32_16x16x32_bf16 v[20:23], v[142:145], v[174:177], v[20:23]
	v_mfma_f32_16x16x32_bf16 v[16:19], v[158:161], v[174:177], v[16:19]
	v_mfma_f32_16x16x32_bf16 v[12:15], v[130:133], v[178:181], v[12:15]
	v_mfma_f32_16x16x32_bf16 v[8:11], v[134:137], v[178:181], v[8:11]
	v_mfma_f32_16x16x32_bf16 v[4:7], v[142:145], v[178:181], v[4:7]
	v_mfma_f32_16x16x32_bf16 v[0:3], v[158:161], v[178:181], v[0:3]
	ds_read_b128 v[130:133], v119
	ds_read_b128 v[134:137], v119 offset:1024
	ds_read_b128 v[140:143], v119 offset:2048
	ds_read_b128 v[144:147], v119 offset:3072
	ds_read_b128 v[96:99], v117
	ds_read_b128 v[158:161], v117 offset:1024
	ds_read_b128 v[166:169], v117 offset:2048
	ds_read_b128 v[174:177], v117 offset:3072
	v_and_b32_e32 v119, 7, v138
	s_waitcnt lgkmcnt(0)
	s_nop 0
	v_mfma_f32_16x16x32_bf16 v[124:127], v[130:133], v[96:99], v[124:127]
	v_mfma_f32_16x16x32_bf16 v[178:181], v[134:137], v[96:99], v[120:123]
	v_mfma_f32_16x16x32_bf16 v[182:185], v[140:143], v[96:99], v[182:185]
	s_nop 5
	v_mul_f32_e32 v128, v125, v125
	v_fmac_f32_e32 v128, v124, v124
	v_fmac_f32_e32 v128, v126, v126
	v_mfma_f32_16x16x32_bf16 v[112:115], v[144:147], v[96:99], v[112:115]
	v_cvt_pk_bf16_f32 v124, v124, v125
	v_cvt_pk_bf16_f32 v125, v126, v127
	v_fmac_f32_e32 v128, v127, v127
	v_mfma_f32_16x16x32_bf16 v[108:111], v[130:133], v[158:161], v[108:111]
	v_cvt_pk_bf16_f32 v127, v180, v181
	v_mfma_f32_16x16x32_bf16 v[104:107], v[134:137], v[158:161], v[104:107]
	v_mfma_f32_16x16x32_bf16 v[96:99], v[140:143], v[158:161], v[100:103]
	v_mfma_f32_16x16x32_bf16 v[100:103], v[144:147], v[158:161], v[162:165]
	v_mfma_f32_16x16x32_bf16 v[92:95], v[130:133], v[166:169], v[92:95]
	v_mfma_f32_16x16x32_bf16 v[88:91], v[134:137], v[166:169], v[88:91]
	v_mfma_f32_16x16x32_bf16 v[84:87], v[140:143], v[166:169], v[84:87]
	v_mfma_f32_16x16x32_bf16 v[80:83], v[144:147], v[166:169], v[80:83]
	ds_read_b128 v[120:123], v117 offset:4096
	ds_read_b128 v[158:161], v117 offset:5120
	ds_read_b128 v[162:165], v117 offset:6144
	ds_read_b128 v[166:169], v117 offset:7168
	s_waitcnt lgkmcnt(0)
	v_bfe_u32 v117, v138, 5, 1
	v_mfma_f32_16x16x32_bf16 v[60:63], v[130:133], v[120:123], v[60:63]
	s_barrier
	v_mfma_f32_16x16x32_bf16 v[56:59], v[134:137], v[120:123], v[56:59]
	v_mfma_f32_16x16x32_bf16 v[52:55], v[140:143], v[120:123], v[52:55]
	v_mfma_f32_16x16x32_bf16 v[48:51], v[144:147], v[120:123], v[48:51]
	v_lshrrev_b32_e32 v121, 1, v138
	v_lshlrev_b32_e32 v120, 7, v116
	v_and_b32_e32 v121, 8, v121
	v_or3_b32 v122, s15, v120, v121
	v_and_b32_e32 v121, 64, v172
	v_xor_b32_e32 v120, 16, v172
	v_add_u32_e32 v121, 64, v121
	v_cmp_lt_i32_e32 vcc, v120, v121
	v_xor_b32_e32 v123, 32, v172
	v_mfma_f32_16x16x32_bf16 v[76:79], v[130:133], v[174:177], v[76:79]
	v_cndmask_b32_e32 v120, v172, v120, vcc
	v_cmp_lt_i32_e32 vcc, v123, v121
	v_lshlrev_b32_e32 v120, 2, v120
	v_mfma_f32_16x16x32_bf16 v[44:47], v[130:133], v[158:161], v[44:47]
	v_cndmask_b32_e32 v121, v172, v123, vcc
	v_bitop3_b32 v123, v117, v138, 7 bitop3:0x78
	v_lshlrev_b32_e32 v123, 4, v123
	v_or_b32_e32 v126, v122, v123
	s_waitcnt vmcnt(0)
	ds_write_b64 v126, v[124:125]
	v_mul_f32_e32 v124, v179, v179
	v_fmac_f32_e32 v124, v178, v178
	v_fmac_f32_e32 v124, v180, v180
	v_bitop3_b32 v125, v117, v119, 2 bitop3:0x36
	v_fmac_f32_e32 v124, v181, v181
	v_lshlrev_b32_e32 v125, 4, v125
	v_add_f32_e32 v124, v128, v124
	v_cvt_pk_bf16_f32 v126, v178, v179
	v_or_b32_e32 v128, v122, v125
	ds_write_b64 v128, v[126:127]
	v_mul_f32_e32 v126, v183, v183
	v_fmac_f32_e32 v126, v182, v182
	v_fmac_f32_e32 v126, v184, v184
	v_fmac_f32_e32 v126, v185, v185
	v_add_f32_e32 v128, v124, v126
	v_bitop3_b32 v124, v117, v119, 4 bitop3:0x36
	v_lshlrev_b32_e32 v124, 4, v124
	v_mfma_f32_16x16x32_bf16 v[28:31], v[130:133], v[162:165], v[28:31]
	v_cvt_pk_bf16_f32 v126, v182, v183
	v_cvt_pk_bf16_f32 v127, v184, v185
	v_lshlrev_b32_e32 v121, 2, v121
	v_mfma_f32_16x16x32_bf16 v[12:15], v[130:133], v[166:169], v[12:15]
	v_or_b32_e32 v130, v122, v124
	ds_write_b64 v130, v[126:127]
	v_mul_f32_e32 v126, v113, v113
	v_fmac_f32_e32 v126, v112, v112
	v_fmac_f32_e32 v126, v114, v114
	v_fmac_f32_e32 v126, v115, v115
	v_add_f32_e32 v128, v128, v126
	v_cvt_pk_bf16_f32 v126, v112, v113
	v_bitop3_b32 v112, v117, v119, 6 bitop3:0x36
	v_lshlrev_b32_e32 v112, 4, v112
	v_cvt_pk_bf16_f32 v127, v114, v115
	v_or_b32_e32 v113, v122, v112
	ds_write_b64 v113, v[126:127]
	ds_bpermute_b32 v113, v120, v128
	v_mfma_f32_16x16x32_bf16 v[72:75], v[134:137], v[174:177], v[72:75]
	v_cmp_gt_u32_e32 vcc, 16, v118
	v_or_b32_e32 v116, s8, v116
	s_waitcnt lgkmcnt(0)
	v_add_f32_e32 v113, v128, v113
	ds_bpermute_b32 v114, v121, v113
	v_mfma_f32_16x16x32_bf16 v[68:71], v[140:143], v[174:177], v[68:71]
	v_mfma_f32_16x16x32_bf16 v[64:67], v[144:147], v[174:177], v[64:67]
	v_mfma_f32_16x16x32_bf16 v[40:43], v[134:137], v[158:161], v[40:43]
	v_mfma_f32_16x16x32_bf16 v[36:39], v[140:143], v[158:161], v[36:39]
	v_mfma_f32_16x16x32_bf16 v[32:35], v[144:147], v[158:161], v[32:35]
	v_mfma_f32_16x16x32_bf16 v[24:27], v[134:137], v[162:165], v[24:27]
	v_mfma_f32_16x16x32_bf16 v[20:23], v[140:143], v[162:165], v[20:23]
	v_mfma_f32_16x16x32_bf16 v[16:19], v[144:147], v[162:165], v[16:19]
	v_mfma_f32_16x16x32_bf16 v[8:11], v[134:137], v[166:169], v[8:11]
	v_mfma_f32_16x16x32_bf16 v[4:7], v[140:143], v[166:169], v[4:7]
	v_mfma_f32_16x16x32_bf16 v[0:3], v[144:147], v[166:169], v[0:3]
	s_and_saveexec_b64 s[6:7], vcc
	s_cbranch_execz .LBB0_1078
	v_ashrrev_i32_e32 v117, 31, v116
	s_waitcnt lgkmcnt(0)
	v_add_f32_e32 v113, v113, v114
	v_lshlrev_b64 v[114:115], 6, v[116:117]
	v_lshl_add_u64 v[114:115], s[64:65], 0, v[114:115]
	v_lshl_add_u64 v[114:115], s[10:11], 2, v[114:115]
	global_store_dword v[114:115], v113, off
